# GEMM load segments: A-fragment ds_reads use one loop-invariant address VGPR + immediate offsets (4 v_add_u32 per iteration removed, no VALU left in load segments); on v103
# speedup vs baseline: 1.0105x; 1.0027x over previous
; #define PG8_STAGE(bufoff, gbase, voff) do { _Pragma("unroll") for (int _i = 0; _i < 2; ++_i) \
;         __builtin_amdgcn_global_load_lds((const unsigned*)((const char*)(gbase) + (voff)[_i]), (PG8_LAS unsigned*)(lds + (bufoff) + ldsw + _i * 8192), 16, 0, 0); } while (0)
; #define PG8_LDA(dst, b, h) do { _Pragma("unroll") for (int m = 0; m < 4; ++m) _Pragma("unroll") for (int k = 0; k < 2; ++k) dst[m][k] = *(const PG8_LAS bf16x8*)(lds + PG8_SA(b, h) + aoff + m * 2048 + k * 1024); } while (0)
; #define PG8_LDB(dst, b, h) do { _Pragma("unroll") for (int n = 0; n < 2; ++n) _Pragma("unroll") for (int k = 0; k < 2; ++k) dst[n][k] = *(const PG8_LAS bf16x8*)(lds + PG8_SB(b, h) + boff + n * 2048 + k * 1024); } while (0)
; #define PG8_SCHED __builtin_amdgcn_sched_barrier(0)
; template <class Epi, class Sched, bool ALIGN_EPI = false, bool SP2 = false>
; __device__ __forceinline__ void gemm_phase(PG8_LAS unsigned char* lds, const Gemm g, const Sched& S, const Epi& E) {
;     ...
;         const bool has_next = S.next(ui + 1, nxt);
;         const char* nA = has_next ? (const char*)g.A + (size_t)nxt.pm * tstep : cA; const char* nB = has_next ? (const char*)g.Bt + (size_t)nxt.pn * tstep : cB;
;         for (int t = 0; t < nt; t += 2) {
;             const bool last = (t == nt - 2);
;             const char* a1 = cA + (size_t)(t + 1) * kstep;
;             const char* a2 = last ? nA : cA + (size_t)(t + 2) * kstep; const char* b2 = last ? nB : cB + (size_t)(t + 2) * kstep;
;             const char* a3 = a2 + kstep; const char* b3 = b2 + kstep;
;             if (last && has_next) S.a_ready(nxt);
;             if constexpr (SP2) {
;             const int rx = (relax && t == 0) ? 1 : 0;
;             PG8_STAGE(PG8_SA(1, 1), a1 + hstep, voffA); PG8_SCHED; PG8_LDB(B0, 0, 0); PG8_LDB(B1, 0, 1); PG8_SCHED; PG8_LDA(At, 0, 0);
;     ...
; #pragma unroll
;         for (int a = 0; a < 2; ++a)
; #pragma unroll
;             for (int b = 0; b < 2; ++b)
; #pragma unroll
;                 for (int m = 0; m < 4; ++m)
; #pragma unroll
;                     for (int n = 0; n < 2; ++n) acc[a][b][m][n] = (f32x4){0.f, 0.f, 0.f, 0.f};
.LBB0_147:
	s_ashr_i32 s21, s20, 31
	s_lshl_b64 s[24:25], s[20:21], 19
	s_add_u32 s24, s39, s24
	s_addc_u32 s25, s38, s25
	s_and_b64 s[26:27], s[22:23], exec
	s_cselect_b32 s21, s25, s1
	s_cselect_b32 s34, s24, s0
	s_ashr_i32 s19, s18, 31
	s_lshl_b64 s[26:27], s[18:19], 19
	s_add_u32 s26, s48, s26
	s_addc_u32 s27, s50, s27
	s_and_b64 s[30:31], s[22:23], exec
	s_cselect_b32 s19, s27, s29
	s_cselect_b32 s41, s26, s28
	s_add_u32 s30, s0, 0x40080
	s_addc_u32 s31, s1, 0
	s_add_u32 s58, s28, 0x100
	v_mov_b32_e32 v0, 0
	s_addc_u32 s59, s29, 0
	s_mov_b32 s60, -2
	s_mov_b64 vcc, 0
	v_mov_b32_e32 v1, v0
	v_mov_b32_e32 v2, v0
	v_mov_b32_e32 v3, v0
	v_mov_b32_e32 v4, v0
	v_mov_b32_e32 v5, v0
	v_mov_b32_e32 v6, v0
	v_mov_b32_e32 v7, v0
	v_mov_b32_e32 v16, v0
	v_mov_b32_e32 v17, v0
	v_mov_b32_e32 v18, v0
	v_mov_b32_e32 v19, v0
	v_mov_b32_e32 v20, v0
	v_mov_b32_e32 v21, v0
	v_mov_b32_e32 v22, v0
	v_mov_b32_e32 v23, v0
	v_mov_b32_e32 v32, v0
	v_mov_b32_e32 v33, v0
	v_mov_b32_e32 v34, v0
	v_mov_b32_e32 v35, v0
	v_mov_b32_e32 v36, v0
	v_mov_b32_e32 v37, v0
	v_mov_b32_e32 v38, v0
	v_mov_b32_e32 v39, v0
	v_mov_b32_e32 v48, v0
	v_mov_b32_e32 v49, v0
	v_mov_b32_e32 v50, v0
	v_mov_b32_e32 v51, v0
	v_mov_b32_e32 v52, v0
	v_mov_b32_e32 v53, v0
	v_mov_b32_e32 v54, v0
	v_mov_b32_e32 v55, v0
	v_mov_b32_e32 v8, v0
	v_mov_b32_e32 v9, v0
	v_mov_b32_e32 v10, v0
	v_mov_b32_e32 v11, v0
	v_mov_b32_e32 v12, v0
	v_mov_b32_e32 v13, v0
	v_mov_b32_e32 v14, v0
	v_mov_b32_e32 v15, v0
	v_mov_b32_e32 v24, v0
	v_mov_b32_e32 v25, v0
	v_mov_b32_e32 v26, v0
	v_mov_b32_e32 v27, v0
	v_mov_b32_e32 v28, v0
	v_mov_b32_e32 v29, v0
	v_mov_b32_e32 v30, v0
	v_mov_b32_e32 v31, v0
	v_mov_b32_e32 v40, v0
	v_mov_b32_e32 v41, v0
	v_mov_b32_e32 v42, v0
	v_mov_b32_e32 v43, v0
	v_mov_b32_e32 v44, v0
	v_mov_b32_e32 v45, v0
	v_mov_b32_e32 v46, v0
	v_mov_b32_e32 v47, v0
	v_mov_b32_e32 v56, v0
	v_mov_b32_e32 v57, v0
	v_mov_b32_e32 v58, v0
	v_mov_b32_e32 v59, v0
	v_mov_b32_e32 v60, v0
	v_mov_b32_e32 v61, v0
	v_mov_b32_e32 v62, v0
	v_mov_b32_e32 v63, v0
	v_mov_b32_e32 v64, v0
	v_mov_b32_e32 v65, v0
	v_mov_b32_e32 v66, v0
	v_mov_b32_e32 v67, v0
	v_mov_b32_e32 v68, v0
	v_mov_b32_e32 v69, v0
	v_mov_b32_e32 v70, v0
	v_mov_b32_e32 v71, v0
	v_mov_b32_e32 v80, v0
	v_mov_b32_e32 v81, v0
	v_mov_b32_e32 v82, v0
	v_mov_b32_e32 v83, v0
	v_mov_b32_e32 v84, v0
	v_mov_b32_e32 v85, v0
	v_mov_b32_e32 v86, v0
	v_mov_b32_e32 v87, v0
	v_mov_b32_e32 v96, v0
	v_mov_b32_e32 v97, v0
	v_mov_b32_e32 v98, v0
	v_mov_b32_e32 v99, v0
	v_mov_b32_e32 v100, v0
	v_mov_b32_e32 v101, v0
	v_mov_b32_e32 v102, v0
	v_mov_b32_e32 v103, v0
	v_mov_b32_e32 v112, v0
	v_mov_b32_e32 v113, v0
	v_mov_b32_e32 v114, v0
	v_mov_b32_e32 v115, v0
	v_mov_b32_e32 v116, v0
	v_mov_b32_e32 v117, v0
	v_mov_b32_e32 v118, v0
	v_mov_b32_e32 v119, v0
	v_mov_b32_e32 v72, v0
	v_mov_b32_e32 v73, v0
	v_mov_b32_e32 v74, v0
	v_mov_b32_e32 v75, v0
	v_mov_b32_e32 v76, v0
	v_mov_b32_e32 v77, v0
	v_mov_b32_e32 v78, v0
	v_mov_b32_e32 v79, v0
	v_mov_b32_e32 v88, v0
	v_mov_b32_e32 v89, v0
	v_mov_b32_e32 v90, v0
	v_mov_b32_e32 v91, v0
	v_mov_b32_e32 v92, v0
	v_mov_b32_e32 v93, v0
	v_mov_b32_e32 v94, v0
	v_mov_b32_e32 v95, v0
	v_mov_b32_e32 v104, v0
	v_mov_b32_e32 v105, v0
	v_mov_b32_e32 v106, v0
	v_mov_b32_e32 v107, v0
	v_mov_b32_e32 v108, v0
	v_mov_b32_e32 v109, v0
	v_mov_b32_e32 v110, v0
	v_mov_b32_e32 v111, v0
	v_mov_b32_e32 v120, v0
	v_mov_b32_e32 v121, v0
	v_mov_b32_e32 v122, v0
	v_mov_b32_e32 v123, v0
	v_mov_b32_e32 v124, v0
	v_mov_b32_e32 v125, v0
	v_mov_b32_e32 v126, v0
	v_mov_b32_e32 v127, v0
	v_lshl_add_u64 v[128:129], s[30:31], 0, v[140:141]
	v_lshl_add_u64 v[130:131], s[30:31], 0, v[142:143]
	v_add_u32_e32 v128, 0x10000, v172
.LBB0_148:
	s_add_u32 s28, s0, vcc_lo
	s_addc_u32 s29, s1, vcc_hi
	s_add_u32 s30, s28, 0x100
	s_addc_u32 s31, s29, 0
	s_add_u32 s98, s28, 0x40080
	s_addc_u32 s99, s29, 0
	s_add_u32 s61, s58, vcc_lo
	s_addc_u32 s65, s59, vcc_hi
	s_cmp_eq_u32 vcc_lo, 0
	s_cselect_b64 s[28:29], -1, 0
	s_and_b64 s[66:67], s[42:43], s[28:29]
	s_cmpk_eq_i32 vcc_lo, 0x700
	s_cselect_b32 s31, s21, s31
	s_cselect_b32 s30, s34, s30
	s_cselect_b32 s29, s19, s65
	s_cselect_b32 s28, s41, s61
	s_add_i32 s61, 0, 0x10000
	s_add_i32 s65, 0, 0x14000
	ds_read_b128 v[144:147], v128
	ds_read_b128 v[148:151], v128 offset:1024
	ds_read_b128 v[152:155], v128 offset:2048
	ds_read_b128 v[156:159], v128 offset:3072
	ds_read_b128 v[160:163], v128 offset:16384
	ds_read_b128 v[164:167], v128 offset:17408
	ds_read_b128 v[168:171], v128 offset:18432
	ds_read_b128 v[174:177], v128 offset:19456
	ds_read_b128 v[178:181], v173
	ds_read_b128 v[182:185], v173 offset:1024
	ds_read_b128 v[186:189], v173 offset:2048
	ds_read_b128 v[204:207], v173 offset:3072
	ds_read_b128 v[208:211], v173 offset:4096
	ds_read_b128 v[212:215], v173 offset:5120
	ds_read_b128 v[216:219], v173 offset:6144
	s_add_i32 m0, s9, 0xc000
	s_and_b32 s70, s66, 1
	global_load_lds_dwordx4 v132, s[98:99]
	s_add_i32 m0, s9, 0xe000
	ds_read_b128 v[220:223], v173 offset:7168
	global_load_lds_dwordx4 v136, s[98:99]
	s_cmp_lg_i32 s70, 0
	s_cbranch_scc1 .Lpg8rx0
	s_waitcnt vmcnt(8)

; #define PG8_STAGE(bufoff, gbase, voff) do { _Pragma("unroll") for (int _i = 0; _i < 2; ++_i) \
;         __builtin_amdgcn_global_load_lds((const unsigned*)((const char*)(gbase) + (voff)[_i]), (PG8_LAS unsigned*)(lds + (bufoff) + ldsw + _i * 8192), 16, 0, 0); } while (0)
; #define PG8_LDA(dst, b, h) do { _Pragma("unroll") for (int m = 0; m < 4; ++m) _Pragma("unroll") for (int k = 0; k < 2; ++k) dst[m][k] = *(const PG8_LAS bf16x8*)(lds + PG8_SA(b, h) + aoff + m * 2048 + k * 1024); } while (0)
; #define PG8_LDB(dst, b, h) do { _Pragma("unroll") for (int n = 0; n < 2; ++n) _Pragma("unroll") for (int k = 0; k < 2; ++k) dst[n][k] = *(const PG8_LAS bf16x8*)(lds + PG8_SB(b, h) + boff + n * 2048 + k * 1024); } while (0)
; #define PG8_MMA(ai, bj, At, Bt) do { __builtin_amdgcn_s_setprio(1); _Pragma("unroll") for (int m = 0; m < 4; ++m) _Pragma("unroll") for (int n = 0; n < 2; ++n) _Pragma("unroll") for (int k = 0; k < 2; ++k) \
;         acc[ai][bj][m][n] = __builtin_amdgcn_mfma_f32_16x16x32_bf16(Bt[n][k], At[m][k], acc[ai][bj][m][n], 0, 0, 0); __builtin_amdgcn_s_setprio(0); } while (0)
; #define PG8_WAIT_V(n) asm volatile("s_waitcnt vmcnt(" #n ")" ::: "memory")
; #define PG8_WAIT_L(n) asm volatile("s_waitcnt lgkmcnt(" #n ")" ::: "memory")
; #define PG8_WAIT_V8_UNLESS(flag) asm volatile("s_cmp_lg_i32 %0, 0\n\ts_cbranch_scc1 .Lpg8rx%=\n\ts_waitcnt vmcnt(8)\n.Lpg8rx%=:" :: "s"(__builtin_amdgcn_readfirstlane(flag)) : "scc", "memory")
; #define PG8_BAR __builtin_amdgcn_s_barrier()
; #define PG8_SCHED __builtin_amdgcn_sched_barrier(0)
; template <class Epi, class Sched, bool ALIGN_EPI = false, bool SP2 = false>
; __device__ __forceinline__ void gemm_phase(PG8_LAS unsigned char* lds, const Gemm g, const Sched& S, const Epi& E) {
;     ...
;             PG8_WAIT_V8_UNLESS(rx); PG8_WAIT_L(0); PG8_BAR; PG8_MMA(1, 0, At, B0); PG8_MMA(1, 1, At, B1); PG8_BAR; PG8_SCHED;
;             PG8_STAGE(PG8_SA(0, 1), a2 + hstep, voffA); PG8_SCHED; PG8_LDB(B0, 1, 0); PG8_LDB(B1, 1, 1); PG8_SCHED; PG8_LDA(At, 1, 0);
;             PG8_WAIT_V(8); PG8_WAIT_L(0); PG8_BAR; PG8_MMA(0, 0, At, B0); PG8_MMA(0, 1, At, B1); PG8_BAR; PG8_SCHED;
.Lpg8rx1:
	s_waitcnt lgkmcnt(0)
	s_setprio 1
	s_barrier
	v_mfma_f32_16x16x32_bf16 v[60:63], v[144:147], v[178:181], v[60:63]
	v_mfma_f32_16x16x32_bf16 v[56:59], v[152:155], v[178:181], v[56:59]
	v_mfma_f32_16x16x32_bf16 v[44:47], v[144:147], v[186:189], v[44:47]
	v_mfma_f32_16x16x32_bf16 v[40:43], v[152:155], v[186:189], v[40:43]
	v_mfma_f32_16x16x32_bf16 v[28:31], v[144:147], v[208:211], v[28:31]
	v_mfma_f32_16x16x32_bf16 v[24:27], v[152:155], v[208:211], v[24:27]
	v_mfma_f32_16x16x32_bf16 v[12:15], v[144:147], v[216:219], v[12:15]
	v_mfma_f32_16x16x32_bf16 v[8:11], v[152:155], v[216:219], v[8:11]
	v_mfma_f32_16x16x32_bf16 v[60:63], v[148:151], v[182:185], v[60:63]
	v_mfma_f32_16x16x32_bf16 v[56:59], v[156:159], v[182:185], v[56:59]
	v_mfma_f32_16x16x32_bf16 v[44:47], v[148:151], v[204:207], v[44:47]
	v_mfma_f32_16x16x32_bf16 v[40:43], v[156:159], v[204:207], v[40:43]
	v_mfma_f32_16x16x32_bf16 v[28:31], v[148:151], v[212:215], v[28:31]
	v_mfma_f32_16x16x32_bf16 v[24:27], v[156:159], v[212:215], v[24:27]
	v_mfma_f32_16x16x32_bf16 v[12:15], v[148:151], v[220:223], v[12:15]
	v_mfma_f32_16x16x32_bf16 v[8:11], v[156:159], v[220:223], v[8:11]
	v_mfma_f32_16x16x32_bf16 v[52:55], v[160:163], v[178:181], v[52:55]
	v_mfma_f32_16x16x32_bf16 v[48:51], v[168:171], v[178:181], v[48:51]
	v_mfma_f32_16x16x32_bf16 v[36:39], v[160:163], v[186:189], v[36:39]
	v_mfma_f32_16x16x32_bf16 v[32:35], v[168:171], v[186:189], v[32:35]
	v_mfma_f32_16x16x32_bf16 v[20:23], v[160:163], v[208:211], v[20:23]
	v_mfma_f32_16x16x32_bf16 v[16:19], v[168:171], v[208:211], v[16:19]
	v_mfma_f32_16x16x32_bf16 v[4:7], v[160:163], v[216:219], v[4:7]
	v_mfma_f32_16x16x32_bf16 v[0:3], v[168:171], v[216:219], v[0:3]
	v_mfma_f32_16x16x32_bf16 v[52:55], v[164:167], v[182:185], v[52:55]
	v_mfma_f32_16x16x32_bf16 v[48:51], v[174:177], v[182:185], v[48:51]
	v_mfma_f32_16x16x32_bf16 v[36:39], v[164:167], v[204:207], v[36:39]
	v_mfma_f32_16x16x32_bf16 v[32:35], v[174:177], v[204:207], v[32:35]
	v_mfma_f32_16x16x32_bf16 v[20:23], v[164:167], v[212:215], v[20:23]
	v_mfma_f32_16x16x32_bf16 v[16:19], v[174:177], v[212:215], v[16:19]
	v_mfma_f32_16x16x32_bf16 v[4:7], v[164:167], v[220:223], v[4:7]
	v_mfma_f32_16x16x32_bf16 v[0:3], v[174:177], v[220:223], v[0:3]
	s_setprio 0
	s_barrier
	s_mov_b64 s[98:99], s[30:31]
	s_add_u32 s100, s30, 0x40000
	s_addc_u32 s101, s31, 0
	s_add_i32 s30, 0, 0x18000
	s_add_i32 s31, 0, 0x1c000
	ds_read_b128 v[144:147], v128 offset:32768
	ds_read_b128 v[148:151], v128 offset:33792
	ds_read_b128 v[152:155], v128 offset:34816
	ds_read_b128 v[156:159], v128 offset:35840
	ds_read_b128 v[160:163], v128 offset:49152
	ds_read_b128 v[164:167], v128 offset:50176
	ds_read_b128 v[168:171], v128 offset:51200
	ds_read_b128 v[174:177], v128 offset:52224
	ds_read_b128 v[178:181], v173 offset:32768
	ds_read_b128 v[182:185], v173 offset:33792
	ds_read_b128 v[186:189], v173 offset:34816
	ds_read_b128 v[204:207], v173 offset:35840
	ds_read_b128 v[208:211], v173 offset:36864
	ds_read_b128 v[212:215], v173 offset:37888
	s_mov_b32 m0, s52
	ds_read_b128 v[216:219], v173 offset:38912
	global_load_lds_dwordx4 v132, s[100:101]
	s_mov_b32 m0, s53
	ds_read_b128 v[220:223], v173 offset:39936
	global_load_lds_dwordx4 v136, s[100:101]
	s_waitcnt vmcnt(8)
	s_waitcnt lgkmcnt(0)
	s_setprio 1
	s_barrier
	v_mfma_f32_16x16x32_bf16 v[124:127], v[144:147], v[178:181], v[124:127]
	v_mfma_f32_16x16x32_bf16 v[120:123], v[152:155], v[178:181], v[120:123]
	v_mfma_f32_16x16x32_bf16 v[108:111], v[144:147], v[186:189], v[108:111]
	v_mfma_f32_16x16x32_bf16 v[104:107], v[152:155], v[186:189], v[104:107]
	v_mfma_f32_16x16x32_bf16 v[92:95], v[144:147], v[208:211], v[92:95]
	v_mfma_f32_16x16x32_bf16 v[88:91], v[152:155], v[208:211], v[88:91]
	v_mfma_f32_16x16x32_bf16 v[76:79], v[144:147], v[216:219], v[76:79]
	v_mfma_f32_16x16x32_bf16 v[72:75], v[152:155], v[216:219], v[72:75]
	v_mfma_f32_16x16x32_bf16 v[124:127], v[148:151], v[182:185], v[124:127]
	v_mfma_f32_16x16x32_bf16 v[120:123], v[156:159], v[182:185], v[120:123]
	v_mfma_f32_16x16x32_bf16 v[108:111], v[148:151], v[204:207], v[108:111]
	v_mfma_f32_16x16x32_bf16 v[104:107], v[156:159], v[204:207], v[104:107]
	v_mfma_f32_16x16x32_bf16 v[92:95], v[148:151], v[212:215], v[92:95]
	v_mfma_f32_16x16x32_bf16 v[88:91], v[156:159], v[212:215], v[88:91]
	v_mfma_f32_16x16x32_bf16 v[76:79], v[148:151], v[220:223], v[76:79]
	v_mfma_f32_16x16x32_bf16 v[72:75], v[156:159], v[220:223], v[72:75]
	v_mfma_f32_16x16x32_bf16 v[116:119], v[160:163], v[178:181], v[116:119]
	v_mfma_f32_16x16x32_bf16 v[112:115], v[168:171], v[178:181], v[112:115]
	v_mfma_f32_16x16x32_bf16 v[100:103], v[160:163], v[186:189], v[100:103]
	v_mfma_f32_16x16x32_bf16 v[96:99], v[168:171], v[186:189], v[96:99]
	v_mfma_f32_16x16x32_bf16 v[84:87], v[160:163], v[208:211], v[84:87]
	v_mfma_f32_16x16x32_bf16 v[80:83], v[168:171], v[208:211], v[80:83]
	v_mfma_f32_16x16x32_bf16 v[68:71], v[160:163], v[216:219], v[68:71]
	v_mfma_f32_16x16x32_bf16 v[64:67], v[168:171], v[216:219], v[64:67]
	v_mfma_f32_16x16x32_bf16 v[116:119], v[164:167], v[182:185], v[116:119]
	v_mfma_f32_16x16x32_bf16 v[112:115], v[174:177], v[182:185], v[112:115]
	v_mfma_f32_16x16x32_bf16 v[100:103], v[164:167], v[204:207], v[100:103]
	v_mfma_f32_16x16x32_bf16 v[96:99], v[174:177], v[204:207], v[96:99]
	v_mfma_f32_16x16x32_bf16 v[84:87], v[164:167], v[212:215], v[84:87]
	v_mfma_f32_16x16x32_bf16 v[80:83], v[174:177], v[212:215], v[80:83]
	v_mfma_f32_16x16x32_bf16 v[68:71], v[164:167], v[220:223], v[68:71]
	v_mfma_f32_16x16x32_bf16 v[64:67], v[174:177], v[220:223], v[64:67]
	s_setprio 0
	s_barrier
; #define PG8_STAGE(bufoff, gbase, voff) do { _Pragma("unroll") for (int _i = 0; _i < 2; ++_i) \
;         __builtin_amdgcn_global_load_lds((const unsigned*)((const char*)(gbase) + (voff)[_i]), (PG8_LAS unsigned*)(lds + (bufoff) + ldsw + _i * 8192), 16, 0, 0); } while (0)
; #define PG8_LDA(dst, b, h) do { _Pragma("unroll") for (int m = 0; m < 4; ++m) _Pragma("unroll") for (int k = 0; k < 2; ++k) dst[m][k] = *(const PG8_LAS bf16x8*)(lds + PG8_SA(b, h) + aoff + m * 2048 + k * 1024); } while (0)
; #define PG8_MMA(ai, bj, At, Bt) do { __builtin_amdgcn_s_setprio(1); _Pragma("unroll") for (int m = 0; m < 4; ++m) _Pragma("unroll") for (int n = 0; n < 2; ++n) _Pragma("unroll") for (int k = 0; k < 2; ++k) \
;         acc[ai][bj][m][n] = __builtin_amdgcn_mfma_f32_16x16x32_bf16(Bt[n][k], At[m][k], acc[ai][bj][m][n], 0, 0, 0); __builtin_amdgcn_s_setprio(0); } while (0)
; #define PG8_WAIT_V(n) asm volatile("s_waitcnt vmcnt(" #n ")" ::: "memory")
; #define PG8_WAIT_L(n) asm volatile("s_waitcnt lgkmcnt(" #n ")" ::: "memory")
; #define PG8_BAR __builtin_amdgcn_s_barrier()
; #define PG8_SCHED __builtin_amdgcn_sched_barrier(0)
; template <class Epi, class Sched, bool ALIGN_EPI = false, bool SP2 = false>
; __device__ __forceinline__ void gemm_phase(PG8_LAS unsigned char* lds, const Gemm g, const Sched& S, const Epi& E) {
;     ...
;             PG8_STAGE(PG8_SB(1, 0), b3, voffB); PG8_STAGE(PG8_SB(1, 1), b3 + hstep, voffB); PG8_STAGE(PG8_SA(1, 0), a3, voffA); PG8_SCHED; PG8_LDA(At, 1, 1);
;             PG8_WAIT_V(8); PG8_WAIT_L(0); PG8_BAR; PG8_MMA(1, 0, At, B0); PG8_MMA(1, 1, At, B1); PG8_BAR; PG8_SCHED;
;     ...
;         if constexpr (ALIGN_EPI) { if (wr == 0) PG8_BAR; }
	ds_read_b128 v[178:181], v173 offset:49152
	ds_read_b128 v[182:185], v173 offset:50176
	s_add_u32 s100, s28, 0x80
	s_addc_u32 s101, s29, 0
	s_add_u32 s28, s28, 0x40080
	s_addc_u32 s29, s29, 0
	s_add_u32 s98, s98, 0x80
	s_addc_u32 s99, s99, 0
	s_add_i32 m0, s30, s46
	ds_read_b128 v[186:189], v173 offset:51200
	global_load_lds_dwordx4 v134, s[100:101]
	s_add_i32 m0, m0, 0x2000
	ds_read_b128 v[204:207], v173 offset:52224
	global_load_lds_dwordx4 v138, s[100:101]
	s_add_i32 m0, s31, s46
	ds_read_b128 v[208:211], v173 offset:53248
	global_load_lds_dwordx4 v134, s[28:29]
	s_add_i32 m0, m0, 0x2000
	ds_read_b128 v[212:215], v173 offset:54272
	global_load_lds_dwordx4 v138, s[28:29]
	s_mov_b32 m0, s54
	ds_read_b128 v[216:219], v173 offset:55296
	global_load_lds_dwordx4 v132, s[98:99]
	s_mov_b32 m0, s55
	ds_read_b128 v[220:223], v173 offset:56320
	global_load_lds_dwordx4 v136, s[98:99]
	s_waitcnt vmcnt(8)
	s_waitcnt lgkmcnt(0)
	s_setprio 1
	s_barrier
	v_mfma_f32_16x16x32_bf16 v[60:63], v[144:147], v[178:181], v[60:63]
	v_mfma_f32_16x16x32_bf16 v[56:59], v[152:155], v[178:181], v[56:59]
	v_mfma_f32_16x16x32_bf16 v[44:47], v[144:147], v[186:189], v[44:47]
	v_mfma_f32_16x16x32_bf16 v[40:43], v[152:155], v[186:189], v[40:43]
	v_mfma_f32_16x16x32_bf16 v[28:31], v[144:147], v[208:211], v[28:31]
	v_mfma_f32_16x16x32_bf16 v[24:27], v[152:155], v[208:211], v[24:27]
	v_mfma_f32_16x16x32_bf16 v[12:15], v[144:147], v[216:219], v[12:15]
	v_mfma_f32_16x16x32_bf16 v[8:11], v[152:155], v[216:219], v[8:11]
	v_mfma_f32_16x16x32_bf16 v[60:63], v[148:151], v[182:185], v[60:63]
	v_mfma_f32_16x16x32_bf16 v[56:59], v[156:159], v[182:185], v[56:59]
	v_mfma_f32_16x16x32_bf16 v[44:47], v[148:151], v[204:207], v[44:47]
	v_mfma_f32_16x16x32_bf16 v[40:43], v[156:159], v[204:207], v[40:43]
	v_mfma_f32_16x16x32_bf16 v[28:31], v[148:151], v[212:215], v[28:31]
	v_mfma_f32_16x16x32_bf16 v[24:27], v[156:159], v[212:215], v[24:27]
	v_mfma_f32_16x16x32_bf16 v[12:15], v[148:151], v[220:223], v[12:15]
	v_mfma_f32_16x16x32_bf16 v[8:11], v[156:159], v[220:223], v[8:11]
	v_mfma_f32_16x16x32_bf16 v[52:55], v[160:163], v[178:181], v[52:55]
	v_mfma_f32_16x16x32_bf16 v[48:51], v[168:171], v[178:181], v[48:51]
	v_mfma_f32_16x16x32_bf16 v[36:39], v[160:163], v[186:189], v[36:39]
	v_mfma_f32_16x16x32_bf16 v[32:35], v[168:171], v[186:189], v[32:35]
	v_mfma_f32_16x16x32_bf16 v[20:23], v[160:163], v[208:211], v[20:23]
	v_mfma_f32_16x16x32_bf16 v[16:19], v[168:171], v[208:211], v[16:19]
	v_mfma_f32_16x16x32_bf16 v[4:7], v[160:163], v[216:219], v[4:7]
	v_mfma_f32_16x16x32_bf16 v[0:3], v[168:171], v[216:219], v[0:3]
	v_mfma_f32_16x16x32_bf16 v[52:55], v[164:167], v[182:185], v[52:55]
	v_mfma_f32_16x16x32_bf16 v[48:51], v[174:177], v[182:185], v[48:51]
	v_mfma_f32_16x16x32_bf16 v[36:39], v[164:167], v[204:207], v[36:39]
	v_mfma_f32_16x16x32_bf16 v[32:35], v[174:177], v[204:207], v[32:35]
	v_mfma_f32_16x16x32_bf16 v[20:23], v[164:167], v[212:215], v[20:23]
	v_mfma_f32_16x16x32_bf16 v[16:19], v[174:177], v[212:215], v[16:19]
	v_mfma_f32_16x16x32_bf16 v[4:7], v[164:167], v[220:223], v[4:7]
	v_mfma_f32_16x16x32_bf16 v[0:3], v[174:177], v[220:223], v[0:3]
	s_setprio 0
	s_barrier
	s_add_i32 s60, s60, 2
	s_add_u32 vcc_lo, vcc_lo, 0x100
	s_addc_u32 vcc_hi, vcc_hi, 0
	s_cmp_gt_u32 s60, 13
	s_cbranch_scc0 .LBB0_148
	s_and_b64 vcc, exec, s[62:63]
	s_cbranch_vccz .LBB0_151
	s_barrier

; #define PG8_STAGE(bufoff, gbase, voff) do { _Pragma("unroll") for (int _i = 0; _i < 2; ++_i) \
;         __builtin_amdgcn_global_load_lds((const unsigned*)((const char*)(gbase) + (voff)[_i]), (PG8_LAS unsigned*)(lds + (bufoff) + ldsw + _i * 8192), 16, 0, 0); } while (0)
; #define PG8_LDA(dst, b, h) do { _Pragma("unroll") for (int m = 0; m < 4; ++m) _Pragma("unroll") for (int k = 0; k < 2; ++k) dst[m][k] = *(const PG8_LAS bf16x8*)(lds + PG8_SA(b, h) + aoff + m * 2048 + k * 1024); } while (0)
; #define PG8_LDB(dst, b, h) do { _Pragma("unroll") for (int n = 0; n < 2; ++n) _Pragma("unroll") for (int k = 0; k < 2; ++k) dst[n][k] = *(const PG8_LAS bf16x8*)(lds + PG8_SB(b, h) + boff + n * 2048 + k * 1024); } while (0)
; #define PG8_SCHED __builtin_amdgcn_sched_barrier(0)
; template <class Epi, class Sched, bool ALIGN_EPI = false, bool SP2 = false>
; __device__ __forceinline__ void gemm_phase(PG8_LAS unsigned char* lds, const Gemm g, const Sched& S, const Epi& E) {
;     ...
;         const bool has_next = S.next(ui + 1, nxt);
;         const char* nA = has_next ? (const char*)g.A + (size_t)nxt.pm * tstep : cA; const char* nB = has_next ? (const char*)g.Bt + (size_t)nxt.pn * tstep : cB;
;         for (int t = 0; t < nt; t += 2) {
;             const bool last = (t == nt - 2);
;             const char* a1 = cA + (size_t)(t + 1) * kstep;
;             const char* a2 = last ? nA : cA + (size_t)(t + 2) * kstep; const char* b2 = last ? nB : cB + (size_t)(t + 2) * kstep;
;             const char* a3 = a2 + kstep; const char* b3 = b2 + kstep;
;             if (last && has_next) S.a_ready(nxt);
;             if constexpr (SP2) {
;             const int rx = (relax && t == 0) ? 1 : 0;
;             PG8_STAGE(PG8_SA(1, 1), a1 + hstep, voffA); PG8_SCHED; PG8_LDB(B0, 0, 0); PG8_LDB(B1, 0, 1); PG8_SCHED; PG8_LDA(At, 0, 0);
;     ...
; #pragma unroll
;         for (int a = 0; a < 2; ++a)
; #pragma unroll
;             for (int b = 0; b < 2; ++b)
; #pragma unroll
;                 for (int m = 0; m < 4; ++m)
; #pragma unroll
;                     for (int n = 0; n < 2; ++n) acc[a][b][m][n] = (f32x4){0.f, 0.f, 0.f, 0.f};
.LBB0_513:
	s_ashr_i32 s19, s18, 31
	s_lshl_b64 s[22:23], s[18:19], 19
	s_add_u32 s22, s4, s22
	s_addc_u32 s23, s5, s23
	s_and_b64 s[24:25], s[20:21], exec
	s_cselect_b32 s19, s23, s1
	s_cselect_b32 s27, s22, s0
	s_ashr_i32 s17, s16, 31
	s_lshl_b64 s[24:25], s[16:17], 19
	s_add_u32 s24, s37, s24
	s_addc_u32 s25, s38, s25
	s_and_b64 s[30:31], s[20:21], exec
	s_cselect_b32 s17, s25, s29
	s_cselect_b32 s55, s24, s28
	s_add_u32 s56, s28, 0x100
	s_addc_u32 s57, s29, 0
	s_add_u32 s28, s0, 0x40080
	s_addc_u32 s29, s1, 0
	v_mov_b32_e32 v0, 0
	v_lshl_add_u64 v[116:117], s[28:29], 0, v[210:211]
	v_lshl_add_u64 v[118:119], s[28:29], 0, v[212:213]
	s_mov_b32 s58, -2
	s_mov_b64 s[62:63], 0
	s_waitcnt lgkmcnt(0)
	v_mov_b32_e32 v1, v0
	v_mov_b32_e32 v2, v0
	v_mov_b32_e32 v3, v0
	v_mov_b32_e32 v4, v0
	v_mov_b32_e32 v5, v0
	v_mov_b32_e32 v6, v0
	v_mov_b32_e32 v7, v0
	v_mov_b32_e32 v16, v0
	v_mov_b32_e32 v17, v0
	v_mov_b32_e32 v18, v0
	v_mov_b32_e32 v19, v0
	v_mov_b32_e32 v20, v0
	v_mov_b32_e32 v21, v0
	v_mov_b32_e32 v22, v0
	v_mov_b32_e32 v23, v0
	v_mov_b32_e32 v32, v0
	v_mov_b32_e32 v33, v0
	v_mov_b32_e32 v34, v0
	v_mov_b32_e32 v35, v0
	v_mov_b32_e32 v36, v0
	v_mov_b32_e32 v37, v0
	v_mov_b32_e32 v38, v0
	v_mov_b32_e32 v39, v0
	v_mov_b32_e32 v48, v0
	v_mov_b32_e32 v49, v0
	v_mov_b32_e32 v50, v0
	v_mov_b32_e32 v51, v0
	v_mov_b32_e32 v52, v0
	v_mov_b32_e32 v53, v0
	v_mov_b32_e32 v54, v0
	v_mov_b32_e32 v55, v0
	v_mov_b32_e32 v8, v0
	v_mov_b32_e32 v9, v0
	v_mov_b32_e32 v10, v0
	v_mov_b32_e32 v11, v0
	v_mov_b32_e32 v12, v0
	v_mov_b32_e32 v13, v0
	v_mov_b32_e32 v14, v0
	v_mov_b32_e32 v15, v0
	v_mov_b32_e32 v24, v0
	v_mov_b32_e32 v25, v0
	v_mov_b32_e32 v26, v0
	v_mov_b32_e32 v27, v0
	v_mov_b32_e32 v28, v0
	v_mov_b32_e32 v29, v0
	v_mov_b32_e32 v30, v0
	v_mov_b32_e32 v31, v0
	v_mov_b32_e32 v40, v0
	v_mov_b32_e32 v41, v0
	v_mov_b32_e32 v42, v0
	v_mov_b32_e32 v43, v0
	v_mov_b32_e32 v44, v0
	v_mov_b32_e32 v45, v0
	v_mov_b32_e32 v46, v0
	v_mov_b32_e32 v47, v0
	v_mov_b32_e32 v56, v0
	v_mov_b32_e32 v57, v0
	v_mov_b32_e32 v58, v0
	v_mov_b32_e32 v59, v0
	v_mov_b32_e32 v60, v0
	v_mov_b32_e32 v61, v0
	v_mov_b32_e32 v62, v0
	v_mov_b32_e32 v63, v0
	v_mov_b32_e32 v64, v0
	v_mov_b32_e32 v65, v0
	v_mov_b32_e32 v66, v0
	v_mov_b32_e32 v67, v0
	v_mov_b32_e32 v68, v0
	v_mov_b32_e32 v69, v0
	v_mov_b32_e32 v70, v0
	v_mov_b32_e32 v71, v0
	v_mov_b32_e32 v80, v0
	v_mov_b32_e32 v81, v0
	v_mov_b32_e32 v82, v0
	v_mov_b32_e32 v83, v0
	v_mov_b32_e32 v84, v0
	v_mov_b32_e32 v85, v0
	v_mov_b32_e32 v86, v0
	v_mov_b32_e32 v87, v0
	v_mov_b32_e32 v96, v0
	v_mov_b32_e32 v97, v0
	v_mov_b32_e32 v98, v0
	v_mov_b32_e32 v99, v0
	v_mov_b32_e32 v100, v0
	v_mov_b32_e32 v101, v0
	v_mov_b32_e32 v102, v0
	v_mov_b32_e32 v103, v0
	v_mov_b32_e32 v112, v0
	v_mov_b32_e32 v113, v0
	v_mov_b32_e32 v114, v0
	v_mov_b32_e32 v115, v0
	v_mov_b32_e32 v124, v0
	v_mov_b32_e32 v125, v0
	v_mov_b32_e32 v126, v0
	v_mov_b32_e32 v127, v0
	v_mov_b32_e32 v72, v0
	v_mov_b32_e32 v73, v0
	v_mov_b32_e32 v74, v0
	v_mov_b32_e32 v75, v0
	v_mov_b32_e32 v76, v0
	v_mov_b32_e32 v77, v0
	v_mov_b32_e32 v78, v0
	v_mov_b32_e32 v79, v0
	v_mov_b32_e32 v88, v0
	v_mov_b32_e32 v89, v0
	v_mov_b32_e32 v90, v0
	v_mov_b32_e32 v91, v0
	v_mov_b32_e32 v92, v0
	v_mov_b32_e32 v93, v0
	v_mov_b32_e32 v94, v0
	v_mov_b32_e32 v95, v0
	v_mov_b32_e32 v104, v0
	v_mov_b32_e32 v105, v0
	v_mov_b32_e32 v106, v0
	v_mov_b32_e32 v107, v0
	v_mov_b32_e32 v108, v0
	v_mov_b32_e32 v109, v0
	v_mov_b32_e32 v110, v0
	v_mov_b32_e32 v111, v0
	v_mov_b32_e32 v148, v0
	v_mov_b32_e32 v149, v0
	v_mov_b32_e32 v150, v0
	v_mov_b32_e32 v151, v0
	v_mov_b32_e32 v152, v0
	v_mov_b32_e32 v153, v0
	v_mov_b32_e32 v154, v0
	v_mov_b32_e32 v155, v0
	v_add_u32_e32 v116, 0x10000, v247
.LBB0_514:
	s_add_u32 s28, s0, s62
	s_addc_u32 s29, s1, s63
	s_add_u32 s30, s28, 0x100
	s_addc_u32 s31, s29, 0
	s_add_u32 s98, s28, 0x40080
	s_addc_u32 s99, s29, 0
	s_add_u32 s59, s56, s62
	s_addc_u32 s65, s57, s63
	s_cmp_eq_u32 s62, 0
	s_cselect_b64 s[28:29], -1, 0
	s_and_b64 s[60:61], s[42:43], s[28:29]
	s_cmpk_eq_i32 s62, 0x700
	s_cselect_b32 s31, s19, s31
	s_cselect_b32 s30, s27, s30
	s_cselect_b32 s29, s17, s65
	s_cselect_b32 s28, s55, s59
	s_add_i32 s59, 0, 0x10000
	s_add_i32 s65, 0, 0x14000
	ds_read_b128 v[120:123], v116
	ds_read_b128 v[128:131], v116 offset:1024
	ds_read_b128 v[132:135], v116 offset:2048
	ds_read_b128 v[136:139], v116 offset:3072
	ds_read_b128 v[140:143], v116 offset:16384
	ds_read_b128 v[144:147], v116 offset:17408
	ds_read_b128 v[156:159], v116 offset:18432
	ds_read_b128 v[160:163], v116 offset:19456
	ds_read_b128 v[164:167], v248
	ds_read_b128 v[168:171], v248 offset:1024
	ds_read_b128 v[172:175], v248 offset:2048
	ds_read_b128 v[176:179], v248 offset:3072
	ds_read_b128 v[180:183], v248 offset:4096
	ds_read_b128 v[184:187], v248 offset:5120
	ds_read_b128 v[188:191], v248 offset:6144
	s_add_i32 m0, s41, 0xc000
	s_and_b32 s66, s60, 1
	global_load_lds_dwordx4 v204, s[98:99]
	s_add_i32 m0, s41, 0xe000
	ds_read_b128 v[214:217], v248 offset:7168
	global_load_lds_dwordx4 v206, s[98:99]
	s_cmp_lg_i32 s66, 0
	s_cbranch_scc1 .Lpg8rx2
	s_waitcnt vmcnt(8)

; #define PG8_STAGE(bufoff, gbase, voff) do { _Pragma("unroll") for (int _i = 0; _i < 2; ++_i) \
;         __builtin_amdgcn_global_load_lds((const unsigned*)((const char*)(gbase) + (voff)[_i]), (PG8_LAS unsigned*)(lds + (bufoff) + ldsw + _i * 8192), 16, 0, 0); } while (0)
; #define PG8_LDA(dst, b, h) do { _Pragma("unroll") for (int m = 0; m < 4; ++m) _Pragma("unroll") for (int k = 0; k < 2; ++k) dst[m][k] = *(const PG8_LAS bf16x8*)(lds + PG8_SA(b, h) + aoff + m * 2048 + k * 1024); } while (0)
; #define PG8_LDB(dst, b, h) do { _Pragma("unroll") for (int n = 0; n < 2; ++n) _Pragma("unroll") for (int k = 0; k < 2; ++k) dst[n][k] = *(const PG8_LAS bf16x8*)(lds + PG8_SB(b, h) + boff + n * 2048 + k * 1024); } while (0)
; #define PG8_MMA(ai, bj, At, Bt) do { __builtin_amdgcn_s_setprio(1); _Pragma("unroll") for (int m = 0; m < 4; ++m) _Pragma("unroll") for (int n = 0; n < 2; ++n) _Pragma("unroll") for (int k = 0; k < 2; ++k) \
;         acc[ai][bj][m][n] = __builtin_amdgcn_mfma_f32_16x16x32_bf16(Bt[n][k], At[m][k], acc[ai][bj][m][n], 0, 0, 0); __builtin_amdgcn_s_setprio(0); } while (0)
; #define PG8_WAIT_V(n) asm volatile("s_waitcnt vmcnt(" #n ")" ::: "memory")
; #define PG8_WAIT_L(n) asm volatile("s_waitcnt lgkmcnt(" #n ")" ::: "memory")
; #define PG8_WAIT_V8_UNLESS(flag) asm volatile("s_cmp_lg_i32 %0, 0\n\ts_cbranch_scc1 .Lpg8rx%=\n\ts_waitcnt vmcnt(8)\n.Lpg8rx%=:" :: "s"(__builtin_amdgcn_readfirstlane(flag)) : "scc", "memory")
; #define PG8_BAR __builtin_amdgcn_s_barrier()
; #define PG8_SCHED __builtin_amdgcn_sched_barrier(0)
; template <class Epi, class Sched, bool ALIGN_EPI = false, bool SP2 = false>
; __device__ __forceinline__ void gemm_phase(PG8_LAS unsigned char* lds, const Gemm g, const Sched& S, const Epi& E) {
;     ...
;             PG8_WAIT_V8_UNLESS(rx); PG8_WAIT_L(0); PG8_BAR; PG8_MMA(1, 0, At, B0); PG8_MMA(1, 1, At, B1); PG8_BAR; PG8_SCHED;
;             PG8_STAGE(PG8_SA(0, 1), a2 + hstep, voffA); PG8_SCHED; PG8_LDB(B0, 1, 0); PG8_LDB(B1, 1, 1); PG8_SCHED; PG8_LDA(At, 1, 0);
;             PG8_WAIT_V(8); PG8_WAIT_L(0); PG8_BAR; PG8_MMA(0, 0, At, B0); PG8_MMA(0, 1, At, B1); PG8_BAR; PG8_SCHED;
.Lpg8rx3:
	s_waitcnt lgkmcnt(0)
	s_setprio 1
	s_barrier
	v_mfma_f32_16x16x32_bf16 v[60:63], v[120:123], v[164:167], v[60:63]
	v_mfma_f32_16x16x32_bf16 v[56:59], v[132:135], v[164:167], v[56:59]
	v_mfma_f32_16x16x32_bf16 v[44:47], v[120:123], v[172:175], v[44:47]
	v_mfma_f32_16x16x32_bf16 v[40:43], v[132:135], v[172:175], v[40:43]
	v_mfma_f32_16x16x32_bf16 v[28:31], v[120:123], v[180:183], v[28:31]
	v_mfma_f32_16x16x32_bf16 v[24:27], v[132:135], v[180:183], v[24:27]
	v_mfma_f32_16x16x32_bf16 v[12:15], v[120:123], v[188:191], v[12:15]
	v_mfma_f32_16x16x32_bf16 v[8:11], v[132:135], v[188:191], v[8:11]
	v_mfma_f32_16x16x32_bf16 v[60:63], v[128:131], v[168:171], v[60:63]
	v_mfma_f32_16x16x32_bf16 v[56:59], v[136:139], v[168:171], v[56:59]
	v_mfma_f32_16x16x32_bf16 v[44:47], v[128:131], v[176:179], v[44:47]
	v_mfma_f32_16x16x32_bf16 v[40:43], v[136:139], v[176:179], v[40:43]
	v_mfma_f32_16x16x32_bf16 v[28:31], v[128:131], v[184:187], v[28:31]
	v_mfma_f32_16x16x32_bf16 v[24:27], v[136:139], v[184:187], v[24:27]
	v_mfma_f32_16x16x32_bf16 v[12:15], v[128:131], v[214:217], v[12:15]
	v_mfma_f32_16x16x32_bf16 v[8:11], v[136:139], v[214:217], v[8:11]
	v_mfma_f32_16x16x32_bf16 v[52:55], v[140:143], v[164:167], v[52:55]
	v_mfma_f32_16x16x32_bf16 v[48:51], v[156:159], v[164:167], v[48:51]
	v_mfma_f32_16x16x32_bf16 v[36:39], v[140:143], v[172:175], v[36:39]
	v_mfma_f32_16x16x32_bf16 v[32:35], v[156:159], v[172:175], v[32:35]
	v_mfma_f32_16x16x32_bf16 v[20:23], v[140:143], v[180:183], v[20:23]
	v_mfma_f32_16x16x32_bf16 v[16:19], v[156:159], v[180:183], v[16:19]
	v_mfma_f32_16x16x32_bf16 v[4:7], v[140:143], v[188:191], v[4:7]
	v_mfma_f32_16x16x32_bf16 v[0:3], v[156:159], v[188:191], v[0:3]
	v_mfma_f32_16x16x32_bf16 v[52:55], v[144:147], v[168:171], v[52:55]
	v_mfma_f32_16x16x32_bf16 v[48:51], v[160:163], v[168:171], v[48:51]
	v_mfma_f32_16x16x32_bf16 v[36:39], v[144:147], v[176:179], v[36:39]
	v_mfma_f32_16x16x32_bf16 v[32:35], v[160:163], v[176:179], v[32:35]
	v_mfma_f32_16x16x32_bf16 v[20:23], v[144:147], v[184:187], v[20:23]
	v_mfma_f32_16x16x32_bf16 v[16:19], v[160:163], v[184:187], v[16:19]
	v_mfma_f32_16x16x32_bf16 v[4:7], v[144:147], v[214:217], v[4:7]
	v_mfma_f32_16x16x32_bf16 v[0:3], v[160:163], v[214:217], v[0:3]
	s_setprio 0
	s_barrier
	s_mov_b64 s[98:99], s[30:31]
	s_add_u32 s100, s30, 0x40000
	s_addc_u32 s101, s31, 0
	s_add_i32 s30, 0, 0x18000
	s_add_i32 s31, 0, 0x1c000
	ds_read_b128 v[120:123], v116 offset:32768
	ds_read_b128 v[128:131], v116 offset:33792
	ds_read_b128 v[132:135], v116 offset:34816
	ds_read_b128 v[136:139], v116 offset:35840
	ds_read_b128 v[140:143], v116 offset:49152
	ds_read_b128 v[144:147], v116 offset:50176
	ds_read_b128 v[156:159], v116 offset:51200
	ds_read_b128 v[160:163], v116 offset:52224
	ds_read_b128 v[164:167], v248 offset:32768
	ds_read_b128 v[168:171], v248 offset:33792
	ds_read_b128 v[172:175], v248 offset:34816
	ds_read_b128 v[176:179], v248 offset:35840
	ds_read_b128 v[180:183], v248 offset:36864
	ds_read_b128 v[184:187], v248 offset:37888
	s_mov_b32 m0, s46
	ds_read_b128 v[188:191], v248 offset:38912
	global_load_lds_dwordx4 v204, s[100:101]
	s_mov_b32 m0, s48
	ds_read_b128 v[214:217], v248 offset:39936
	global_load_lds_dwordx4 v206, s[100:101]
	s_waitcnt vmcnt(8)
	s_waitcnt lgkmcnt(0)
	s_setprio 1
	s_barrier
	v_mfma_f32_16x16x32_bf16 v[152:155], v[120:123], v[164:167], v[152:155]
	v_mfma_f32_16x16x32_bf16 v[148:151], v[132:135], v[164:167], v[148:151]
	v_mfma_f32_16x16x32_bf16 v[108:111], v[120:123], v[172:175], v[108:111]
	v_mfma_f32_16x16x32_bf16 v[104:107], v[132:135], v[172:175], v[104:107]
	v_mfma_f32_16x16x32_bf16 v[92:95], v[120:123], v[180:183], v[92:95]
	v_mfma_f32_16x16x32_bf16 v[88:91], v[132:135], v[180:183], v[88:91]
	v_mfma_f32_16x16x32_bf16 v[76:79], v[120:123], v[188:191], v[76:79]
	v_mfma_f32_16x16x32_bf16 v[72:75], v[132:135], v[188:191], v[72:75]
	v_mfma_f32_16x16x32_bf16 v[152:155], v[128:131], v[168:171], v[152:155]
	v_mfma_f32_16x16x32_bf16 v[148:151], v[136:139], v[168:171], v[148:151]
	v_mfma_f32_16x16x32_bf16 v[108:111], v[128:131], v[176:179], v[108:111]
	v_mfma_f32_16x16x32_bf16 v[104:107], v[136:139], v[176:179], v[104:107]
	v_mfma_f32_16x16x32_bf16 v[92:95], v[128:131], v[184:187], v[92:95]
	v_mfma_f32_16x16x32_bf16 v[88:91], v[136:139], v[184:187], v[88:91]
	v_mfma_f32_16x16x32_bf16 v[76:79], v[128:131], v[214:217], v[76:79]
	v_mfma_f32_16x16x32_bf16 v[72:75], v[136:139], v[214:217], v[72:75]
	v_mfma_f32_16x16x32_bf16 v[124:127], v[140:143], v[164:167], v[124:127]
	v_mfma_f32_16x16x32_bf16 v[112:115], v[156:159], v[164:167], v[112:115]
	v_mfma_f32_16x16x32_bf16 v[100:103], v[140:143], v[172:175], v[100:103]
	v_mfma_f32_16x16x32_bf16 v[96:99], v[156:159], v[172:175], v[96:99]
	v_mfma_f32_16x16x32_bf16 v[84:87], v[140:143], v[180:183], v[84:87]
	v_mfma_f32_16x16x32_bf16 v[80:83], v[156:159], v[180:183], v[80:83]
	v_mfma_f32_16x16x32_bf16 v[68:71], v[140:143], v[188:191], v[68:71]
	v_mfma_f32_16x16x32_bf16 v[64:67], v[156:159], v[188:191], v[64:67]
	v_mfma_f32_16x16x32_bf16 v[124:127], v[144:147], v[168:171], v[124:127]
	v_mfma_f32_16x16x32_bf16 v[112:115], v[160:163], v[168:171], v[112:115]
	v_mfma_f32_16x16x32_bf16 v[100:103], v[144:147], v[176:179], v[100:103]
	v_mfma_f32_16x16x32_bf16 v[96:99], v[160:163], v[176:179], v[96:99]
	v_mfma_f32_16x16x32_bf16 v[84:87], v[144:147], v[184:187], v[84:87]
	v_mfma_f32_16x16x32_bf16 v[80:83], v[160:163], v[184:187], v[80:83]
	v_mfma_f32_16x16x32_bf16 v[68:71], v[144:147], v[214:217], v[68:71]
	v_mfma_f32_16x16x32_bf16 v[64:67], v[160:163], v[214:217], v[64:67]
	s_setprio 0
	s_barrier
; #define PG8_STAGE(bufoff, gbase, voff) do { _Pragma("unroll") for (int _i = 0; _i < 2; ++_i) \
;         __builtin_amdgcn_global_load_lds((const unsigned*)((const char*)(gbase) + (voff)[_i]), (PG8_LAS unsigned*)(lds + (bufoff) + ldsw + _i * 8192), 16, 0, 0); } while (0)
; #define PG8_LDA(dst, b, h) do { _Pragma("unroll") for (int m = 0; m < 4; ++m) _Pragma("unroll") for (int k = 0; k < 2; ++k) dst[m][k] = *(const PG8_LAS bf16x8*)(lds + PG8_SA(b, h) + aoff + m * 2048 + k * 1024); } while (0)
; #define PG8_MMA(ai, bj, At, Bt) do { __builtin_amdgcn_s_setprio(1); _Pragma("unroll") for (int m = 0; m < 4; ++m) _Pragma("unroll") for (int n = 0; n < 2; ++n) _Pragma("unroll") for (int k = 0; k < 2; ++k) \
;         acc[ai][bj][m][n] = __builtin_amdgcn_mfma_f32_16x16x32_bf16(Bt[n][k], At[m][k], acc[ai][bj][m][n], 0, 0, 0); __builtin_amdgcn_s_setprio(0); } while (0)
; #define PG8_WAIT_V(n) asm volatile("s_waitcnt vmcnt(" #n ")" ::: "memory")
; #define PG8_WAIT_L(n) asm volatile("s_waitcnt lgkmcnt(" #n ")" ::: "memory")
; #define PG8_BAR __builtin_amdgcn_s_barrier()
; #define PG8_SCHED __builtin_amdgcn_sched_barrier(0)
; template <class Epi, class Sched, bool ALIGN_EPI = false, bool SP2 = false>
; __device__ __forceinline__ void gemm_phase(PG8_LAS unsigned char* lds, const Gemm g, const Sched& S, const Epi& E) {
;     ...
;             PG8_STAGE(PG8_SB(1, 0), b3, voffB); PG8_STAGE(PG8_SB(1, 1), b3 + hstep, voffB); PG8_STAGE(PG8_SA(1, 0), a3, voffA); PG8_SCHED; PG8_LDA(At, 1, 1);
;             PG8_WAIT_V(8); PG8_WAIT_L(0); PG8_BAR; PG8_MMA(1, 0, At, B0); PG8_MMA(1, 1, At, B1); PG8_BAR; PG8_SCHED;
;     ...
;         if constexpr (ALIGN_EPI) { if (wr == 0) PG8_BAR; }
	ds_read_b128 v[164:167], v248 offset:49152
	ds_read_b128 v[168:171], v248 offset:50176
	s_add_u32 s100, s28, 0x80
	s_addc_u32 s101, s29, 0
	s_add_u32 s28, s28, 0x40080
	s_addc_u32 s29, s29, 0
	s_add_u32 s98, s98, 0x80
	s_addc_u32 s99, s99, 0
	s_add_i32 m0, s30, s39
	ds_read_b128 v[172:175], v248 offset:51200
	global_load_lds_dwordx4 v194, s[100:101]
	s_add_i32 m0, m0, 0x2000
	ds_read_b128 v[176:179], v248 offset:52224
	global_load_lds_dwordx4 v208, s[100:101]
	s_add_i32 m0, s31, s39
	ds_read_b128 v[180:183], v248 offset:53248
	global_load_lds_dwordx4 v194, s[28:29]
	s_add_i32 m0, m0, 0x2000
	ds_read_b128 v[184:187], v248 offset:54272
	global_load_lds_dwordx4 v208, s[28:29]
	s_mov_b32 m0, s50
	ds_read_b128 v[188:191], v248 offset:55296
	global_load_lds_dwordx4 v204, s[98:99]
	s_mov_b32 m0, s51
	ds_read_b128 v[214:217], v248 offset:56320
	global_load_lds_dwordx4 v206, s[98:99]
	s_waitcnt vmcnt(8)
	s_waitcnt lgkmcnt(0)
	s_setprio 1
	s_barrier
	v_mfma_f32_16x16x32_bf16 v[60:63], v[120:123], v[164:167], v[60:63]
	v_mfma_f32_16x16x32_bf16 v[56:59], v[132:135], v[164:167], v[56:59]
	v_mfma_f32_16x16x32_bf16 v[44:47], v[120:123], v[172:175], v[44:47]
	v_mfma_f32_16x16x32_bf16 v[40:43], v[132:135], v[172:175], v[40:43]
	v_mfma_f32_16x16x32_bf16 v[28:31], v[120:123], v[180:183], v[28:31]
	v_mfma_f32_16x16x32_bf16 v[24:27], v[132:135], v[180:183], v[24:27]
	v_mfma_f32_16x16x32_bf16 v[12:15], v[120:123], v[188:191], v[12:15]
	v_mfma_f32_16x16x32_bf16 v[8:11], v[132:135], v[188:191], v[8:11]
	v_mfma_f32_16x16x32_bf16 v[60:63], v[128:131], v[168:171], v[60:63]
	v_mfma_f32_16x16x32_bf16 v[56:59], v[136:139], v[168:171], v[56:59]
	v_mfma_f32_16x16x32_bf16 v[44:47], v[128:131], v[176:179], v[44:47]
	v_mfma_f32_16x16x32_bf16 v[40:43], v[136:139], v[176:179], v[40:43]
	v_mfma_f32_16x16x32_bf16 v[28:31], v[128:131], v[184:187], v[28:31]
	v_mfma_f32_16x16x32_bf16 v[24:27], v[136:139], v[184:187], v[24:27]
	v_mfma_f32_16x16x32_bf16 v[12:15], v[128:131], v[214:217], v[12:15]
	v_mfma_f32_16x16x32_bf16 v[8:11], v[136:139], v[214:217], v[8:11]
	v_mfma_f32_16x16x32_bf16 v[52:55], v[140:143], v[164:167], v[52:55]
	v_mfma_f32_16x16x32_bf16 v[48:51], v[156:159], v[164:167], v[48:51]
	v_mfma_f32_16x16x32_bf16 v[36:39], v[140:143], v[172:175], v[36:39]
	v_mfma_f32_16x16x32_bf16 v[32:35], v[156:159], v[172:175], v[32:35]
	v_mfma_f32_16x16x32_bf16 v[20:23], v[140:143], v[180:183], v[20:23]
	v_mfma_f32_16x16x32_bf16 v[16:19], v[156:159], v[180:183], v[16:19]
	v_mfma_f32_16x16x32_bf16 v[4:7], v[140:143], v[188:191], v[4:7]
	v_mfma_f32_16x16x32_bf16 v[0:3], v[156:159], v[188:191], v[0:3]
	v_mfma_f32_16x16x32_bf16 v[52:55], v[144:147], v[168:171], v[52:55]
	v_mfma_f32_16x16x32_bf16 v[48:51], v[160:163], v[168:171], v[48:51]
	v_mfma_f32_16x16x32_bf16 v[36:39], v[144:147], v[176:179], v[36:39]
	v_mfma_f32_16x16x32_bf16 v[32:35], v[160:163], v[176:179], v[32:35]
	v_mfma_f32_16x16x32_bf16 v[20:23], v[144:147], v[184:187], v[20:23]
	v_mfma_f32_16x16x32_bf16 v[16:19], v[160:163], v[184:187], v[16:19]
	v_mfma_f32_16x16x32_bf16 v[4:7], v[144:147], v[214:217], v[4:7]
	v_mfma_f32_16x16x32_bf16 v[0:3], v[160:163], v[214:217], v[0:3]
	s_setprio 0
	s_barrier
	s_add_i32 s58, s58, 2
	s_add_u32 s62, s62, 0x100
	s_addc_u32 s63, s63, 0
	s_cmp_gt_u32 s58, 13
	s_cbranch_scc0 .LBB0_514
	s_and_b64 vcc, exec, s[14:15]
	s_cbranch_vccz .LBB0_517
	s_barrier

; #define PG8_STAGE(bufoff, gbase, voff) do { _Pragma("unroll") for (int _i = 0; _i < 2; ++_i) \
;         __builtin_amdgcn_global_load_lds((const unsigned*)((const char*)(gbase) + (voff)[_i]), (PG8_LAS unsigned*)(lds + (bufoff) + ldsw + _i * 8192), 16, 0, 0); } while (0)
; #define PG8_LDA(dst, b, h) do { _Pragma("unroll") for (int m = 0; m < 4; ++m) _Pragma("unroll") for (int k = 0; k < 2; ++k) dst[m][k] = *(const PG8_LAS bf16x8*)(lds + PG8_SA(b, h) + aoff + m * 2048 + k * 1024); } while (0)
; #define PG8_LDB(dst, b, h) do { _Pragma("unroll") for (int n = 0; n < 2; ++n) _Pragma("unroll") for (int k = 0; k < 2; ++k) dst[n][k] = *(const PG8_LAS bf16x8*)(lds + PG8_SB(b, h) + boff + n * 2048 + k * 1024); } while (0)
; #define PG8_SCHED __builtin_amdgcn_sched_barrier(0)
; template <class Epi, class Sched, bool ALIGN_EPI = false, bool SP2 = false>
; __device__ __forceinline__ void gemm_phase(PG8_LAS unsigned char* lds, const Gemm g, const Sched& S, const Epi& E) {
;     ...
;         const bool has_next = S.next(ui + 1, nxt);
;         const char* nA = has_next ? (const char*)g.A + (size_t)nxt.pm * tstep : cA; const char* nB = has_next ? (const char*)g.Bt + (size_t)nxt.pn * tstep : cB;
;         for (int t = 0; t < nt; t += 2) {
;             const bool last = (t == nt - 2);
;             const char* a1 = cA + (size_t)(t + 1) * kstep;
;             const char* a2 = last ? nA : cA + (size_t)(t + 2) * kstep; const char* b2 = last ? nB : cB + (size_t)(t + 2) * kstep;
;             const char* a3 = a2 + kstep; const char* b3 = b2 + kstep;
;             if (last && has_next) S.a_ready(nxt);
;             if constexpr (SP2) {
;             const int rx = (relax && t == 0) ? 1 : 0;
;             PG8_STAGE(PG8_SA(1, 1), a1 + hstep, voffA); PG8_SCHED; PG8_LDB(B0, 0, 0); PG8_LDB(B1, 0, 1); PG8_SCHED; PG8_LDA(At, 0, 0);
;     ...
; #pragma unroll
;         for (int a = 0; a < 2; ++a)
; #pragma unroll
;             for (int b = 0; b < 2; ++b)
; #pragma unroll
;                 for (int m = 0; m < 4; ++m)
; #pragma unroll
;                     for (int n = 0; n < 2; ++n) acc[a][b][m][n] = (f32x4){0.f, 0.f, 0.f, 0.f};
.LBB0_610:
	s_ashr_i32 s13, s12, 31
	s_lshl_b64 s[16:17], s[12:13], 19
	s_add_u32 s16, s39, s16
	s_addc_u32 s17, s42, s17
	s_and_b64 s[18:19], s[14:15], exec
	s_cselect_b32 s13, s17, s25
	s_cselect_b32 s54, s16, s24
	s_ashr_i32 s11, s10, 31
	s_lshl_b64 s[18:19], s[10:11], 19
	s_add_u32 s18, s43, s18
	s_addc_u32 s19, s44, s19
	s_and_b64 s[30:31], s[14:15], exec
	s_cselect_b32 s11, s19, s29
	s_cselect_b32 s55, s18, s28
	s_add_u32 s30, s24, 0x40080
	s_addc_u32 s31, s25, 0
	s_add_u32 s56, s28, 0x100
	v_mov_b32_e32 v0, 0
	v_lshl_add_u64 v[128:129], s[30:31], 0, v[160:161]
	v_lshl_add_u64 v[130:131], s[30:31], 0, v[162:163]
	s_addc_u32 s57, s29, 0
	s_mov_b32 s58, -2
	s_mov_b64 s[40:41], 0
	v_mov_b32_e32 v1, v0
	v_mov_b32_e32 v2, v0
	v_mov_b32_e32 v3, v0
	v_mov_b32_e32 v4, v0
	v_mov_b32_e32 v5, v0
	v_mov_b32_e32 v6, v0
	v_mov_b32_e32 v7, v0
	v_mov_b32_e32 v16, v0
	v_mov_b32_e32 v17, v0
	v_mov_b32_e32 v18, v0
	v_mov_b32_e32 v19, v0
	v_mov_b32_e32 v20, v0
	v_mov_b32_e32 v21, v0
	v_mov_b32_e32 v22, v0
	v_mov_b32_e32 v23, v0
	v_mov_b32_e32 v32, v0
	v_mov_b32_e32 v33, v0
	v_mov_b32_e32 v34, v0
	v_mov_b32_e32 v35, v0
	v_mov_b32_e32 v36, v0
	v_mov_b32_e32 v37, v0
	v_mov_b32_e32 v38, v0
	v_mov_b32_e32 v39, v0
	v_mov_b32_e32 v48, v0
	v_mov_b32_e32 v49, v0
	v_mov_b32_e32 v50, v0
	v_mov_b32_e32 v51, v0
	v_mov_b32_e32 v52, v0
	v_mov_b32_e32 v53, v0
	v_mov_b32_e32 v54, v0
	v_mov_b32_e32 v55, v0
	v_mov_b32_e32 v8, v0
	v_mov_b32_e32 v9, v0
	v_mov_b32_e32 v10, v0
	v_mov_b32_e32 v11, v0
	v_mov_b32_e32 v12, v0
	v_mov_b32_e32 v13, v0
	v_mov_b32_e32 v14, v0
	v_mov_b32_e32 v15, v0
	v_mov_b32_e32 v24, v0
	v_mov_b32_e32 v25, v0
	v_mov_b32_e32 v26, v0
	v_mov_b32_e32 v27, v0
	v_mov_b32_e32 v28, v0
	v_mov_b32_e32 v29, v0
	v_mov_b32_e32 v30, v0
	v_mov_b32_e32 v31, v0
	v_mov_b32_e32 v40, v0
	v_mov_b32_e32 v41, v0
	v_mov_b32_e32 v42, v0
	v_mov_b32_e32 v43, v0
	v_mov_b32_e32 v44, v0
	v_mov_b32_e32 v45, v0
	v_mov_b32_e32 v46, v0
	v_mov_b32_e32 v47, v0
	v_mov_b32_e32 v56, v0
	v_mov_b32_e32 v57, v0
	v_mov_b32_e32 v58, v0
	v_mov_b32_e32 v59, v0
	v_mov_b32_e32 v60, v0
	v_mov_b32_e32 v61, v0
	v_mov_b32_e32 v62, v0
	v_mov_b32_e32 v63, v0
	v_mov_b32_e32 v64, v0
	v_mov_b32_e32 v65, v0
	v_mov_b32_e32 v66, v0
	v_mov_b32_e32 v67, v0
	v_mov_b32_e32 v68, v0
	v_mov_b32_e32 v69, v0
	v_mov_b32_e32 v70, v0
	v_mov_b32_e32 v71, v0
	v_mov_b32_e32 v80, v0
	v_mov_b32_e32 v81, v0
	v_mov_b32_e32 v82, v0
	v_mov_b32_e32 v83, v0
	v_mov_b32_e32 v84, v0
	v_mov_b32_e32 v85, v0
	v_mov_b32_e32 v86, v0
	v_mov_b32_e32 v87, v0
	v_mov_b32_e32 v96, v0
	v_mov_b32_e32 v97, v0
	v_mov_b32_e32 v98, v0
	v_mov_b32_e32 v99, v0
	v_mov_b32_e32 v100, v0
	v_mov_b32_e32 v101, v0
	v_mov_b32_e32 v102, v0
	v_mov_b32_e32 v103, v0
	v_mov_b32_e32 v112, v0
	v_mov_b32_e32 v113, v0
	v_mov_b32_e32 v114, v0
	v_mov_b32_e32 v115, v0
	v_mov_b32_e32 v116, v0
	v_mov_b32_e32 v117, v0
	v_mov_b32_e32 v118, v0
	v_mov_b32_e32 v119, v0
	v_mov_b32_e32 v72, v0
	v_mov_b32_e32 v73, v0
	v_mov_b32_e32 v74, v0
	v_mov_b32_e32 v75, v0
	v_mov_b32_e32 v76, v0
	v_mov_b32_e32 v77, v0
	v_mov_b32_e32 v78, v0
	v_mov_b32_e32 v79, v0
	v_mov_b32_e32 v88, v0
	v_mov_b32_e32 v89, v0
	v_mov_b32_e32 v90, v0
	v_mov_b32_e32 v91, v0
	v_mov_b32_e32 v92, v0
	v_mov_b32_e32 v93, v0
	v_mov_b32_e32 v94, v0
	v_mov_b32_e32 v95, v0
	v_mov_b32_e32 v104, v0
	v_mov_b32_e32 v105, v0
	v_mov_b32_e32 v106, v0
	v_mov_b32_e32 v107, v0
	v_mov_b32_e32 v108, v0
	v_mov_b32_e32 v109, v0
	v_mov_b32_e32 v110, v0
	v_mov_b32_e32 v111, v0
	v_mov_b32_e32 v120, v0
	v_mov_b32_e32 v121, v0
	v_mov_b32_e32 v122, v0
	v_mov_b32_e32 v123, v0
	v_mov_b32_e32 v124, v0
	v_mov_b32_e32 v125, v0
	v_mov_b32_e32 v126, v0
	v_mov_b32_e32 v127, v0
	v_add_u32_e32 v128, 0x10000, v183
.LBB0_611:
	s_add_u32 s28, s24, s40
	s_addc_u32 s29, s25, s41
	s_add_u32 s30, s28, 0x100
	s_addc_u32 s31, s29, 0
	s_add_u32 s98, s28, 0x40080
	s_addc_u32 s99, s29, 0
	s_add_u32 s59, s56, s40
	s_addc_u32 s62, s57, s41
	s_cmp_eq_u32 s40, 0
	s_cselect_b64 s[28:29], -1, 0
	s_and_b64 s[60:61], s[26:27], s[28:29]
	s_cmpk_eq_i32 s40, 0x700
	s_cselect_b32 s31, s13, s31
	s_cselect_b32 s30, s54, s30
	s_cselect_b32 s29, s11, s62
	s_cselect_b32 s28, s55, s59
	s_add_i32 s59, 0, 0x10000
	s_add_i32 s62, 0, 0x14000
	ds_read_b128 v[132:135], v128
	ds_read_b128 v[136:139], v128 offset:1024
	ds_read_b128 v[140:143], v128 offset:2048
	ds_read_b128 v[144:147], v128 offset:3072
	ds_read_b128 v[148:151], v128 offset:16384
	ds_read_b128 v[164:167], v128 offset:17408
	ds_read_b128 v[168:171], v128 offset:18432
	ds_read_b128 v[172:175], v128 offset:19456
	ds_read_b128 v[176:179], v185
	ds_read_b128 v[186:189], v185 offset:1024
	ds_read_b128 v[204:207], v185 offset:2048
	ds_read_b128 v[208:211], v185 offset:3072
	ds_read_b128 v[212:215], v185 offset:4096
	ds_read_b128 v[216:219], v185 offset:5120
	ds_read_b128 v[220:223], v185 offset:6144
	s_add_i32 m0, s21, 0xc000
	s_and_b32 s63, s60, 1
	global_load_lds_dwordx4 v152, s[98:99]
	s_add_i32 m0, s21, 0xe000
	ds_read_b128 v[224:227], v185 offset:7168
	global_load_lds_dwordx4 v156, s[98:99]
	s_cmp_lg_i32 s63, 0
	s_cbranch_scc1 .Lpg8rx4
	s_waitcnt vmcnt(8)

; #define PG8_STAGE(bufoff, gbase, voff) do { _Pragma("unroll") for (int _i = 0; _i < 2; ++_i) \
;         __builtin_amdgcn_global_load_lds((const unsigned*)((const char*)(gbase) + (voff)[_i]), (PG8_LAS unsigned*)(lds + (bufoff) + ldsw + _i * 8192), 16, 0, 0); } while (0)
; #define PG8_LDA(dst, b, h) do { _Pragma("unroll") for (int m = 0; m < 4; ++m) _Pragma("unroll") for (int k = 0; k < 2; ++k) dst[m][k] = *(const PG8_LAS bf16x8*)(lds + PG8_SA(b, h) + aoff + m * 2048 + k * 1024); } while (0)
; #define PG8_LDB(dst, b, h) do { _Pragma("unroll") for (int n = 0; n < 2; ++n) _Pragma("unroll") for (int k = 0; k < 2; ++k) dst[n][k] = *(const PG8_LAS bf16x8*)(lds + PG8_SB(b, h) + boff + n * 2048 + k * 1024); } while (0)
; #define PG8_MMA(ai, bj, At, Bt) do { __builtin_amdgcn_s_setprio(1); _Pragma("unroll") for (int m = 0; m < 4; ++m) _Pragma("unroll") for (int n = 0; n < 2; ++n) _Pragma("unroll") for (int k = 0; k < 2; ++k) \
;         acc[ai][bj][m][n] = __builtin_amdgcn_mfma_f32_16x16x32_bf16(Bt[n][k], At[m][k], acc[ai][bj][m][n], 0, 0, 0); __builtin_amdgcn_s_setprio(0); } while (0)
; #define PG8_WAIT_V(n) asm volatile("s_waitcnt vmcnt(" #n ")" ::: "memory")
; #define PG8_WAIT_L(n) asm volatile("s_waitcnt lgkmcnt(" #n ")" ::: "memory")
; #define PG8_WAIT_V8_UNLESS(flag) asm volatile("s_cmp_lg_i32 %0, 0\n\ts_cbranch_scc1 .Lpg8rx%=\n\ts_waitcnt vmcnt(8)\n.Lpg8rx%=:" :: "s"(__builtin_amdgcn_readfirstlane(flag)) : "scc", "memory")
; #define PG8_BAR __builtin_amdgcn_s_barrier()
; #define PG8_SCHED __builtin_amdgcn_sched_barrier(0)
; template <class Epi, class Sched, bool ALIGN_EPI = false, bool SP2 = false>
; __device__ __forceinline__ void gemm_phase(PG8_LAS unsigned char* lds, const Gemm g, const Sched& S, const Epi& E) {
;     ...
;             PG8_WAIT_V8_UNLESS(rx); PG8_WAIT_L(0); PG8_BAR; PG8_MMA(1, 0, At, B0); PG8_MMA(1, 1, At, B1); PG8_BAR; PG8_SCHED;
;             PG8_STAGE(PG8_SA(0, 1), a2 + hstep, voffA); PG8_SCHED; PG8_LDB(B0, 1, 0); PG8_LDB(B1, 1, 1); PG8_SCHED; PG8_LDA(At, 1, 0);
;             PG8_WAIT_V(8); PG8_WAIT_L(0); PG8_BAR; PG8_MMA(0, 0, At, B0); PG8_MMA(0, 1, At, B1); PG8_BAR; PG8_SCHED;
.Lpg8rx5:
	s_waitcnt lgkmcnt(0)
	s_setprio 1
	s_barrier
	v_mfma_f32_16x16x32_bf16 v[60:63], v[132:135], v[176:179], v[60:63]
	v_mfma_f32_16x16x32_bf16 v[56:59], v[140:143], v[176:179], v[56:59]
	v_mfma_f32_16x16x32_bf16 v[44:47], v[132:135], v[204:207], v[44:47]
	v_mfma_f32_16x16x32_bf16 v[40:43], v[140:143], v[204:207], v[40:43]
	v_mfma_f32_16x16x32_bf16 v[28:31], v[132:135], v[212:215], v[28:31]
	v_mfma_f32_16x16x32_bf16 v[24:27], v[140:143], v[212:215], v[24:27]
	v_mfma_f32_16x16x32_bf16 v[12:15], v[132:135], v[220:223], v[12:15]
	v_mfma_f32_16x16x32_bf16 v[8:11], v[140:143], v[220:223], v[8:11]
	v_mfma_f32_16x16x32_bf16 v[60:63], v[136:139], v[186:189], v[60:63]
	v_mfma_f32_16x16x32_bf16 v[56:59], v[144:147], v[186:189], v[56:59]
	v_mfma_f32_16x16x32_bf16 v[44:47], v[136:139], v[208:211], v[44:47]
	v_mfma_f32_16x16x32_bf16 v[40:43], v[144:147], v[208:211], v[40:43]
	v_mfma_f32_16x16x32_bf16 v[28:31], v[136:139], v[216:219], v[28:31]
	v_mfma_f32_16x16x32_bf16 v[24:27], v[144:147], v[216:219], v[24:27]
	v_mfma_f32_16x16x32_bf16 v[12:15], v[136:139], v[224:227], v[12:15]
	v_mfma_f32_16x16x32_bf16 v[8:11], v[144:147], v[224:227], v[8:11]
	v_mfma_f32_16x16x32_bf16 v[52:55], v[148:151], v[176:179], v[52:55]
	v_mfma_f32_16x16x32_bf16 v[48:51], v[168:171], v[176:179], v[48:51]
	v_mfma_f32_16x16x32_bf16 v[36:39], v[148:151], v[204:207], v[36:39]
	v_mfma_f32_16x16x32_bf16 v[32:35], v[168:171], v[204:207], v[32:35]
	v_mfma_f32_16x16x32_bf16 v[20:23], v[148:151], v[212:215], v[20:23]
	v_mfma_f32_16x16x32_bf16 v[16:19], v[168:171], v[212:215], v[16:19]
	v_mfma_f32_16x16x32_bf16 v[4:7], v[148:151], v[220:223], v[4:7]
	v_mfma_f32_16x16x32_bf16 v[0:3], v[168:171], v[220:223], v[0:3]
	v_mfma_f32_16x16x32_bf16 v[52:55], v[164:167], v[186:189], v[52:55]
	v_mfma_f32_16x16x32_bf16 v[48:51], v[172:175], v[186:189], v[48:51]
	v_mfma_f32_16x16x32_bf16 v[36:39], v[164:167], v[208:211], v[36:39]
	v_mfma_f32_16x16x32_bf16 v[32:35], v[172:175], v[208:211], v[32:35]
	v_mfma_f32_16x16x32_bf16 v[20:23], v[164:167], v[216:219], v[20:23]
	v_mfma_f32_16x16x32_bf16 v[16:19], v[172:175], v[216:219], v[16:19]
	v_mfma_f32_16x16x32_bf16 v[4:7], v[164:167], v[224:227], v[4:7]
	v_mfma_f32_16x16x32_bf16 v[0:3], v[172:175], v[224:227], v[0:3]
	s_setprio 0
	s_barrier
	s_mov_b64 s[98:99], s[30:31]
	s_add_u32 s100, s30, 0x40000
	s_addc_u32 s101, s31, 0
	s_add_i32 s30, 0, 0x18000
	s_add_i32 s31, 0, 0x1c000
	ds_read_b128 v[132:135], v128 offset:32768
	ds_read_b128 v[136:139], v128 offset:33792
	ds_read_b128 v[140:143], v128 offset:34816
	ds_read_b128 v[144:147], v128 offset:35840
	ds_read_b128 v[148:151], v128 offset:49152
	ds_read_b128 v[164:167], v128 offset:50176
	ds_read_b128 v[168:171], v128 offset:51200
	ds_read_b128 v[172:175], v128 offset:52224
	ds_read_b128 v[176:179], v185 offset:32768
	ds_read_b128 v[186:189], v185 offset:33792
	ds_read_b128 v[204:207], v185 offset:34816
	ds_read_b128 v[208:211], v185 offset:35840
	ds_read_b128 v[212:215], v185 offset:36864
	ds_read_b128 v[216:219], v185 offset:37888
	s_mov_b32 m0, s46
	ds_read_b128 v[220:223], v185 offset:38912
	global_load_lds_dwordx4 v152, s[100:101]
	s_mov_b32 m0, s48
	ds_read_b128 v[224:227], v185 offset:39936
	global_load_lds_dwordx4 v156, s[100:101]
	s_waitcnt vmcnt(8)
	s_waitcnt lgkmcnt(0)
	s_setprio 1
	s_barrier
	v_mfma_f32_16x16x32_bf16 v[124:127], v[132:135], v[176:179], v[124:127]
	v_mfma_f32_16x16x32_bf16 v[120:123], v[140:143], v[176:179], v[120:123]
	v_mfma_f32_16x16x32_bf16 v[108:111], v[132:135], v[204:207], v[108:111]
	v_mfma_f32_16x16x32_bf16 v[104:107], v[140:143], v[204:207], v[104:107]
	v_mfma_f32_16x16x32_bf16 v[92:95], v[132:135], v[212:215], v[92:95]
	v_mfma_f32_16x16x32_bf16 v[88:91], v[140:143], v[212:215], v[88:91]
	v_mfma_f32_16x16x32_bf16 v[76:79], v[132:135], v[220:223], v[76:79]
	v_mfma_f32_16x16x32_bf16 v[72:75], v[140:143], v[220:223], v[72:75]
	v_mfma_f32_16x16x32_bf16 v[124:127], v[136:139], v[186:189], v[124:127]
	v_mfma_f32_16x16x32_bf16 v[120:123], v[144:147], v[186:189], v[120:123]
	v_mfma_f32_16x16x32_bf16 v[108:111], v[136:139], v[208:211], v[108:111]
	v_mfma_f32_16x16x32_bf16 v[104:107], v[144:147], v[208:211], v[104:107]
	v_mfma_f32_16x16x32_bf16 v[92:95], v[136:139], v[216:219], v[92:95]
	v_mfma_f32_16x16x32_bf16 v[88:91], v[144:147], v[216:219], v[88:91]
	v_mfma_f32_16x16x32_bf16 v[76:79], v[136:139], v[224:227], v[76:79]
	v_mfma_f32_16x16x32_bf16 v[72:75], v[144:147], v[224:227], v[72:75]
	v_mfma_f32_16x16x32_bf16 v[116:119], v[148:151], v[176:179], v[116:119]
	v_mfma_f32_16x16x32_bf16 v[112:115], v[168:171], v[176:179], v[112:115]
	v_mfma_f32_16x16x32_bf16 v[100:103], v[148:151], v[204:207], v[100:103]
	v_mfma_f32_16x16x32_bf16 v[96:99], v[168:171], v[204:207], v[96:99]
	v_mfma_f32_16x16x32_bf16 v[84:87], v[148:151], v[212:215], v[84:87]
	v_mfma_f32_16x16x32_bf16 v[80:83], v[168:171], v[212:215], v[80:83]
	v_mfma_f32_16x16x32_bf16 v[68:71], v[148:151], v[220:223], v[68:71]
	v_mfma_f32_16x16x32_bf16 v[64:67], v[168:171], v[220:223], v[64:67]
	v_mfma_f32_16x16x32_bf16 v[116:119], v[164:167], v[186:189], v[116:119]
	v_mfma_f32_16x16x32_bf16 v[112:115], v[172:175], v[186:189], v[112:115]
	v_mfma_f32_16x16x32_bf16 v[100:103], v[164:167], v[208:211], v[100:103]
	v_mfma_f32_16x16x32_bf16 v[96:99], v[172:175], v[208:211], v[96:99]
	v_mfma_f32_16x16x32_bf16 v[84:87], v[164:167], v[216:219], v[84:87]
	v_mfma_f32_16x16x32_bf16 v[80:83], v[172:175], v[216:219], v[80:83]
	v_mfma_f32_16x16x32_bf16 v[68:71], v[164:167], v[224:227], v[68:71]
	v_mfma_f32_16x16x32_bf16 v[64:67], v[172:175], v[224:227], v[64:67]
	s_setprio 0
	s_barrier
; #define PG8_STAGE(bufoff, gbase, voff) do { _Pragma("unroll") for (int _i = 0; _i < 2; ++_i) \
;         __builtin_amdgcn_global_load_lds((const unsigned*)((const char*)(gbase) + (voff)[_i]), (PG8_LAS unsigned*)(lds + (bufoff) + ldsw + _i * 8192), 16, 0, 0); } while (0)
; #define PG8_LDA(dst, b, h) do { _Pragma("unroll") for (int m = 0; m < 4; ++m) _Pragma("unroll") for (int k = 0; k < 2; ++k) dst[m][k] = *(const PG8_LAS bf16x8*)(lds + PG8_SA(b, h) + aoff + m * 2048 + k * 1024); } while (0)
; #define PG8_MMA(ai, bj, At, Bt) do { __builtin_amdgcn_s_setprio(1); _Pragma("unroll") for (int m = 0; m < 4; ++m) _Pragma("unroll") for (int n = 0; n < 2; ++n) _Pragma("unroll") for (int k = 0; k < 2; ++k) \
;         acc[ai][bj][m][n] = __builtin_amdgcn_mfma_f32_16x16x32_bf16(Bt[n][k], At[m][k], acc[ai][bj][m][n], 0, 0, 0); __builtin_amdgcn_s_setprio(0); } while (0)
; #define PG8_WAIT_V(n) asm volatile("s_waitcnt vmcnt(" #n ")" ::: "memory")
; #define PG8_WAIT_L(n) asm volatile("s_waitcnt lgkmcnt(" #n ")" ::: "memory")
; #define PG8_BAR __builtin_amdgcn_s_barrier()
; #define PG8_SCHED __builtin_amdgcn_sched_barrier(0)
; template <class Epi, class Sched, bool ALIGN_EPI = false, bool SP2 = false>
; __device__ __forceinline__ void gemm_phase(PG8_LAS unsigned char* lds, const Gemm g, const Sched& S, const Epi& E) {
;     ...
;             PG8_STAGE(PG8_SB(1, 0), b3, voffB); PG8_STAGE(PG8_SB(1, 1), b3 + hstep, voffB); PG8_STAGE(PG8_SA(1, 0), a3, voffA); PG8_SCHED; PG8_LDA(At, 1, 1);
;             PG8_WAIT_V(8); PG8_WAIT_L(0); PG8_BAR; PG8_MMA(1, 0, At, B0); PG8_MMA(1, 1, At, B1); PG8_BAR; PG8_SCHED;
;     ...
;         if constexpr (ALIGN_EPI) { if (wr == 0) PG8_BAR; }
	ds_read_b128 v[176:179], v185 offset:49152
	ds_read_b128 v[186:189], v185 offset:50176
	s_add_u32 s100, s28, 0x80
	s_addc_u32 s101, s29, 0
	s_add_u32 s28, s28, 0x40080
	s_addc_u32 s29, s29, 0
	s_add_u32 s98, s98, 0x80
	s_addc_u32 s99, s99, 0
	s_add_i32 m0, s30, s38
	ds_read_b128 v[204:207], v185 offset:51200
	global_load_lds_dwordx4 v154, s[100:101]
	s_add_i32 m0, m0, 0x2000
	ds_read_b128 v[208:211], v185 offset:52224
	global_load_lds_dwordx4 v158, s[100:101]
	s_add_i32 m0, s31, s38
	ds_read_b128 v[212:215], v185 offset:53248
	global_load_lds_dwordx4 v154, s[28:29]
	s_add_i32 m0, m0, 0x2000
	ds_read_b128 v[216:219], v185 offset:54272
	global_load_lds_dwordx4 v158, s[28:29]
	s_mov_b32 m0, s50
	ds_read_b128 v[220:223], v185 offset:55296
	global_load_lds_dwordx4 v152, s[98:99]
	s_mov_b32 m0, s51
	ds_read_b128 v[224:227], v185 offset:56320
	global_load_lds_dwordx4 v156, s[98:99]
	s_waitcnt vmcnt(8)
	s_waitcnt lgkmcnt(0)
	s_setprio 1
	s_barrier
	v_mfma_f32_16x16x32_bf16 v[60:63], v[132:135], v[176:179], v[60:63]
	v_mfma_f32_16x16x32_bf16 v[56:59], v[140:143], v[176:179], v[56:59]
	v_mfma_f32_16x16x32_bf16 v[44:47], v[132:135], v[204:207], v[44:47]
	v_mfma_f32_16x16x32_bf16 v[40:43], v[140:143], v[204:207], v[40:43]
	v_mfma_f32_16x16x32_bf16 v[28:31], v[132:135], v[212:215], v[28:31]
	v_mfma_f32_16x16x32_bf16 v[24:27], v[140:143], v[212:215], v[24:27]
	v_mfma_f32_16x16x32_bf16 v[12:15], v[132:135], v[220:223], v[12:15]
	v_mfma_f32_16x16x32_bf16 v[8:11], v[140:143], v[220:223], v[8:11]
	v_mfma_f32_16x16x32_bf16 v[60:63], v[136:139], v[186:189], v[60:63]
	v_mfma_f32_16x16x32_bf16 v[56:59], v[144:147], v[186:189], v[56:59]
	v_mfma_f32_16x16x32_bf16 v[44:47], v[136:139], v[208:211], v[44:47]
	v_mfma_f32_16x16x32_bf16 v[40:43], v[144:147], v[208:211], v[40:43]
	v_mfma_f32_16x16x32_bf16 v[28:31], v[136:139], v[216:219], v[28:31]
	v_mfma_f32_16x16x32_bf16 v[24:27], v[144:147], v[216:219], v[24:27]
	v_mfma_f32_16x16x32_bf16 v[12:15], v[136:139], v[224:227], v[12:15]
	v_mfma_f32_16x16x32_bf16 v[8:11], v[144:147], v[224:227], v[8:11]
	v_mfma_f32_16x16x32_bf16 v[52:55], v[148:151], v[176:179], v[52:55]
	v_mfma_f32_16x16x32_bf16 v[48:51], v[168:171], v[176:179], v[48:51]
	v_mfma_f32_16x16x32_bf16 v[36:39], v[148:151], v[204:207], v[36:39]
	v_mfma_f32_16x16x32_bf16 v[32:35], v[168:171], v[204:207], v[32:35]
	v_mfma_f32_16x16x32_bf16 v[20:23], v[148:151], v[212:215], v[20:23]
	v_mfma_f32_16x16x32_bf16 v[16:19], v[168:171], v[212:215], v[16:19]
	v_mfma_f32_16x16x32_bf16 v[4:7], v[148:151], v[220:223], v[4:7]
	v_mfma_f32_16x16x32_bf16 v[0:3], v[168:171], v[220:223], v[0:3]
	v_mfma_f32_16x16x32_bf16 v[52:55], v[164:167], v[186:189], v[52:55]
	v_mfma_f32_16x16x32_bf16 v[48:51], v[172:175], v[186:189], v[48:51]
	v_mfma_f32_16x16x32_bf16 v[36:39], v[164:167], v[208:211], v[36:39]
	v_mfma_f32_16x16x32_bf16 v[32:35], v[172:175], v[208:211], v[32:35]
	v_mfma_f32_16x16x32_bf16 v[20:23], v[164:167], v[216:219], v[20:23]
	v_mfma_f32_16x16x32_bf16 v[16:19], v[172:175], v[216:219], v[16:19]
	v_mfma_f32_16x16x32_bf16 v[4:7], v[164:167], v[224:227], v[4:7]
	v_mfma_f32_16x16x32_bf16 v[0:3], v[172:175], v[224:227], v[0:3]
	s_setprio 0
	s_barrier
	s_add_i32 s58, s58, 2
	s_add_u32 s40, s40, 0x100
	s_addc_u32 s41, s41, 0
	s_cmp_gt_u32 s58, 13
	s_cbranch_scc0 .LBB0_611
	s_and_b64 vcc, exec, s[8:9]
	s_cbranch_vccz .LBB0_614
	s_barrier

; #define PG8_STAGE(bufoff, gbase, voff) do { _Pragma("unroll") for (int _i = 0; _i < 2; ++_i) \
;         __builtin_amdgcn_global_load_lds((const unsigned*)((const char*)(gbase) + (voff)[_i]), (PG8_LAS unsigned*)(lds + (bufoff) + ldsw + _i * 8192), 16, 0, 0); } while (0)
; #define PG8_LDA(dst, b, h) do { _Pragma("unroll") for (int m = 0; m < 4; ++m) _Pragma("unroll") for (int k = 0; k < 2; ++k) dst[m][k] = *(const PG8_LAS bf16x8*)(lds + PG8_SA(b, h) + aoff + m * 2048 + k * 1024); } while (0)
; #define PG8_LDB(dst, b, h) do { _Pragma("unroll") for (int n = 0; n < 2; ++n) _Pragma("unroll") for (int k = 0; k < 2; ++k) dst[n][k] = *(const PG8_LAS bf16x8*)(lds + PG8_SB(b, h) + boff + n * 2048 + k * 1024); } while (0)
; #define PG8_SCHED __builtin_amdgcn_sched_barrier(0)
; template <class Epi, class Sched, bool ALIGN_EPI = false, bool SP2 = false>
; __device__ __forceinline__ void gemm_phase(PG8_LAS unsigned char* lds, const Gemm g, const Sched& S, const Epi& E) {
;     ...
;         const bool has_next = S.next(ui + 1, nxt);
;         const char* nA = has_next ? (const char*)g.A + (size_t)nxt.pm * tstep : cA; const char* nB = has_next ? (const char*)g.Bt + (size_t)nxt.pn * tstep : cB;
;         for (int t = 0; t < nt; t += 2) {
;             const bool last = (t == nt - 2);
;             const char* a1 = cA + (size_t)(t + 1) * kstep;
;             const char* a2 = last ? nA : cA + (size_t)(t + 2) * kstep; const char* b2 = last ? nB : cB + (size_t)(t + 2) * kstep;
;             const char* a3 = a2 + kstep; const char* b3 = b2 + kstep;
;             if (last && has_next) S.a_ready(nxt);
;             if constexpr (SP2) {
;             const int rx = (relax && t == 0) ? 1 : 0;
;             PG8_STAGE(PG8_SA(1, 1), a1 + hstep, voffA); PG8_SCHED; PG8_LDB(B0, 0, 0); PG8_LDB(B1, 0, 1); PG8_SCHED; PG8_LDA(At, 0, 0);
;     ...
; #pragma unroll
;         for (int a = 0; a < 2; ++a)
; #pragma unroll
;             for (int b = 0; b < 2; ++b)
; #pragma unroll
;                 for (int m = 0; m < 4; ++m)
; #pragma unroll
;                     for (int n = 0; n < 2; ++n) acc[a][b][m][n] = (f32x4){0.f, 0.f, 0.f, 0.f};
.LBB0_964:
	s_ashr_i32 s15, s14, 31
	s_lshl_b64 s[18:19], s[14:15], 21
	s_add_u32 s18, s2, s18
	s_addc_u32 s19, s3, s19
	s_and_b64 s[20:21], s[16:17], exec
	s_cselect_b32 s15, s19, s1
	s_cselect_b32 s23, s18, s0
	s_ashr_i32 s13, s12, 31
	s_lshl_b64 s[20:21], s[12:13], 21
	s_add_u32 s20, s37, s20
	s_addc_u32 s21, s38, s21
	s_and_b64 s[30:31], s[16:17], exec
	s_cselect_b32 s13, s21, s29
	s_cselect_b32 s53, s20, s28
	s_add_u32 s54, s28, 0x100
	s_addc_u32 s55, s29, 0
	s_add_u32 s28, s0, 0x100080
	s_addc_u32 s29, s1, 0
	v_mov_b32_e32 v0, 0
	v_lshl_add_u64 v[116:117], s[28:29], 0, v[210:211]
	v_lshl_add_u64 v[118:119], s[28:29], 0, v[212:213]
	s_mov_b32 s56, -2
	s_mov_b64 s[40:41], 0
	s_waitcnt lgkmcnt(0)
	v_mov_b32_e32 v1, v0
	v_mov_b32_e32 v2, v0
	v_mov_b32_e32 v3, v0
	v_mov_b32_e32 v4, v0
	v_mov_b32_e32 v5, v0
	v_mov_b32_e32 v6, v0
	v_mov_b32_e32 v7, v0
	v_mov_b32_e32 v16, v0
	v_mov_b32_e32 v17, v0
	v_mov_b32_e32 v18, v0
	v_mov_b32_e32 v19, v0
	v_mov_b32_e32 v20, v0
	v_mov_b32_e32 v21, v0
	v_mov_b32_e32 v22, v0
	v_mov_b32_e32 v23, v0
	v_mov_b32_e32 v32, v0
	v_mov_b32_e32 v33, v0
	v_mov_b32_e32 v34, v0
	v_mov_b32_e32 v35, v0
	v_mov_b32_e32 v36, v0
	v_mov_b32_e32 v37, v0
	v_mov_b32_e32 v38, v0
	v_mov_b32_e32 v39, v0
	v_mov_b32_e32 v48, v0
	v_mov_b32_e32 v49, v0
	v_mov_b32_e32 v50, v0
	v_mov_b32_e32 v51, v0
	v_mov_b32_e32 v52, v0
	v_mov_b32_e32 v53, v0
	v_mov_b32_e32 v54, v0
	v_mov_b32_e32 v55, v0
	v_mov_b32_e32 v8, v0
	v_mov_b32_e32 v9, v0
	v_mov_b32_e32 v10, v0
	v_mov_b32_e32 v11, v0
	v_mov_b32_e32 v12, v0
	v_mov_b32_e32 v13, v0
	v_mov_b32_e32 v14, v0
	v_mov_b32_e32 v15, v0
	v_mov_b32_e32 v24, v0
	v_mov_b32_e32 v25, v0
	v_mov_b32_e32 v26, v0
	v_mov_b32_e32 v27, v0
	v_mov_b32_e32 v28, v0
	v_mov_b32_e32 v29, v0
	v_mov_b32_e32 v30, v0
	v_mov_b32_e32 v31, v0
	v_mov_b32_e32 v40, v0
	v_mov_b32_e32 v41, v0
	v_mov_b32_e32 v42, v0
	v_mov_b32_e32 v43, v0
	v_mov_b32_e32 v44, v0
	v_mov_b32_e32 v45, v0
	v_mov_b32_e32 v46, v0
	v_mov_b32_e32 v47, v0
	v_mov_b32_e32 v56, v0
	v_mov_b32_e32 v57, v0
	v_mov_b32_e32 v58, v0
	v_mov_b32_e32 v59, v0
	v_mov_b32_e32 v60, v0
	v_mov_b32_e32 v61, v0
	v_mov_b32_e32 v62, v0
	v_mov_b32_e32 v63, v0
	v_mov_b32_e32 v64, v0
	v_mov_b32_e32 v65, v0
	v_mov_b32_e32 v66, v0
	v_mov_b32_e32 v67, v0
	v_mov_b32_e32 v68, v0
	v_mov_b32_e32 v69, v0
	v_mov_b32_e32 v70, v0
	v_mov_b32_e32 v71, v0
	v_mov_b32_e32 v80, v0
	v_mov_b32_e32 v81, v0
	v_mov_b32_e32 v82, v0
	v_mov_b32_e32 v83, v0
	v_mov_b32_e32 v84, v0
	v_mov_b32_e32 v85, v0
	v_mov_b32_e32 v86, v0
	v_mov_b32_e32 v87, v0
	v_mov_b32_e32 v96, v0
	v_mov_b32_e32 v97, v0
	v_mov_b32_e32 v98, v0
	v_mov_b32_e32 v99, v0
	v_mov_b32_e32 v100, v0
	v_mov_b32_e32 v101, v0
	v_mov_b32_e32 v102, v0
	v_mov_b32_e32 v103, v0
	v_mov_b32_e32 v112, v0
	v_mov_b32_e32 v113, v0
	v_mov_b32_e32 v114, v0
	v_mov_b32_e32 v115, v0
	v_mov_b32_e32 v124, v0
	v_mov_b32_e32 v125, v0
	v_mov_b32_e32 v126, v0
	v_mov_b32_e32 v127, v0
	v_mov_b32_e32 v72, v0
	v_mov_b32_e32 v73, v0
	v_mov_b32_e32 v74, v0
	v_mov_b32_e32 v75, v0
	v_mov_b32_e32 v76, v0
	v_mov_b32_e32 v77, v0
	v_mov_b32_e32 v78, v0
	v_mov_b32_e32 v79, v0
	v_mov_b32_e32 v88, v0
	v_mov_b32_e32 v89, v0
	v_mov_b32_e32 v90, v0
	v_mov_b32_e32 v91, v0
	v_mov_b32_e32 v92, v0
	v_mov_b32_e32 v93, v0
	v_mov_b32_e32 v94, v0
	v_mov_b32_e32 v95, v0
	v_mov_b32_e32 v104, v0
	v_mov_b32_e32 v105, v0
	v_mov_b32_e32 v106, v0
	v_mov_b32_e32 v107, v0
	v_mov_b32_e32 v108, v0
	v_mov_b32_e32 v109, v0
	v_mov_b32_e32 v110, v0
	v_mov_b32_e32 v111, v0
	v_mov_b32_e32 v148, v0
	v_mov_b32_e32 v149, v0
	v_mov_b32_e32 v150, v0
	v_mov_b32_e32 v151, v0
	v_mov_b32_e32 v152, v0
	v_mov_b32_e32 v153, v0
	v_mov_b32_e32 v154, v0
	v_mov_b32_e32 v155, v0
	v_add_u32_e32 v116, 0x10000, v247
.LBB0_965:
	s_add_u32 s28, s0, s40
	s_addc_u32 s29, s1, s41
	s_add_u32 s30, s28, 0x100
	s_addc_u32 s31, s29, 0
	s_add_u32 s98, s28, 0x100080
	s_addc_u32 s99, s29, 0
	s_add_u32 s57, s54, s40
	s_addc_u32 s60, s55, s41
	s_cmp_eq_u32 s40, 0
	s_cselect_b64 s[28:29], -1, 0
	s_and_b64 s[58:59], s[26:27], s[28:29]
	s_cmpk_eq_i32 s40, 0x1f00
	s_cselect_b32 s31, s15, s31
	s_cselect_b32 s30, s23, s30
	s_cselect_b32 s29, s13, s60
	s_cselect_b32 s28, s53, s57
	s_add_i32 s57, 0, 0x10000
	s_add_i32 s60, 0, 0x14000
	ds_read_b128 v[120:123], v116
	ds_read_b128 v[128:131], v116 offset:1024
	ds_read_b128 v[132:135], v116 offset:2048
	ds_read_b128 v[136:139], v116 offset:3072
	ds_read_b128 v[140:143], v116 offset:16384
	ds_read_b128 v[144:147], v116 offset:17408
	ds_read_b128 v[156:159], v116 offset:18432
	ds_read_b128 v[160:163], v116 offset:19456
	ds_read_b128 v[164:167], v248
	ds_read_b128 v[168:171], v248 offset:1024
	ds_read_b128 v[172:175], v248 offset:2048
	ds_read_b128 v[176:179], v248 offset:3072
	ds_read_b128 v[180:183], v248 offset:4096
	ds_read_b128 v[184:187], v248 offset:5120
	ds_read_b128 v[188:191], v248 offset:6144
	s_add_i32 m0, s25, 0xc000
	s_and_b32 s61, s58, 1
	global_load_lds_dwordx4 v204, s[98:99]
	s_add_i32 m0, s25, 0xe000
	ds_read_b128 v[214:217], v248 offset:7168
	global_load_lds_dwordx4 v206, s[98:99]
	s_cmp_lg_i32 s61, 0
	s_cbranch_scc1 .Lpg8rx6
	s_waitcnt vmcnt(8)

; #define PG8_STAGE(bufoff, gbase, voff) do { _Pragma("unroll") for (int _i = 0; _i < 2; ++_i) \
;         __builtin_amdgcn_global_load_lds((const unsigned*)((const char*)(gbase) + (voff)[_i]), (PG8_LAS unsigned*)(lds + (bufoff) + ldsw + _i * 8192), 16, 0, 0); } while (0)
; #define PG8_LDA(dst, b, h) do { _Pragma("unroll") for (int m = 0; m < 4; ++m) _Pragma("unroll") for (int k = 0; k < 2; ++k) dst[m][k] = *(const PG8_LAS bf16x8*)(lds + PG8_SA(b, h) + aoff + m * 2048 + k * 1024); } while (0)
; #define PG8_LDB(dst, b, h) do { _Pragma("unroll") for (int n = 0; n < 2; ++n) _Pragma("unroll") for (int k = 0; k < 2; ++k) dst[n][k] = *(const PG8_LAS bf16x8*)(lds + PG8_SB(b, h) + boff + n * 2048 + k * 1024); } while (0)
; #define PG8_MMA(ai, bj, At, Bt) do { __builtin_amdgcn_s_setprio(1); _Pragma("unroll") for (int m = 0; m < 4; ++m) _Pragma("unroll") for (int n = 0; n < 2; ++n) _Pragma("unroll") for (int k = 0; k < 2; ++k) \
;         acc[ai][bj][m][n] = __builtin_amdgcn_mfma_f32_16x16x32_bf16(Bt[n][k], At[m][k], acc[ai][bj][m][n], 0, 0, 0); __builtin_amdgcn_s_setprio(0); } while (0)
; #define PG8_WAIT_V(n) asm volatile("s_waitcnt vmcnt(" #n ")" ::: "memory")
; #define PG8_WAIT_L(n) asm volatile("s_waitcnt lgkmcnt(" #n ")" ::: "memory")
; #define PG8_WAIT_V8_UNLESS(flag) asm volatile("s_cmp_lg_i32 %0, 0\n\ts_cbranch_scc1 .Lpg8rx%=\n\ts_waitcnt vmcnt(8)\n.Lpg8rx%=:" :: "s"(__builtin_amdgcn_readfirstlane(flag)) : "scc", "memory")
; #define PG8_BAR __builtin_amdgcn_s_barrier()
; #define PG8_SCHED __builtin_amdgcn_sched_barrier(0)
; template <class Epi, class Sched, bool ALIGN_EPI = false, bool SP2 = false>
; __device__ __forceinline__ void gemm_phase(PG8_LAS unsigned char* lds, const Gemm g, const Sched& S, const Epi& E) {
;     ...
;             PG8_WAIT_V8_UNLESS(rx); PG8_WAIT_L(0); PG8_BAR; PG8_MMA(1, 0, At, B0); PG8_MMA(1, 1, At, B1); PG8_BAR; PG8_SCHED;
;             PG8_STAGE(PG8_SA(0, 1), a2 + hstep, voffA); PG8_SCHED; PG8_LDB(B0, 1, 0); PG8_LDB(B1, 1, 1); PG8_SCHED; PG8_LDA(At, 1, 0);
;             PG8_WAIT_V(8); PG8_WAIT_L(0); PG8_BAR; PG8_MMA(0, 0, At, B0); PG8_MMA(0, 1, At, B1); PG8_BAR; PG8_SCHED;
.Lpg8rx7:
	s_waitcnt lgkmcnt(0)
	s_setprio 1
	s_barrier
	v_mfma_f32_16x16x32_bf16 v[60:63], v[120:123], v[164:167], v[60:63]
	v_mfma_f32_16x16x32_bf16 v[56:59], v[132:135], v[164:167], v[56:59]
	v_mfma_f32_16x16x32_bf16 v[44:47], v[120:123], v[172:175], v[44:47]
	v_mfma_f32_16x16x32_bf16 v[40:43], v[132:135], v[172:175], v[40:43]
	v_mfma_f32_16x16x32_bf16 v[28:31], v[120:123], v[180:183], v[28:31]
	v_mfma_f32_16x16x32_bf16 v[24:27], v[132:135], v[180:183], v[24:27]
	v_mfma_f32_16x16x32_bf16 v[12:15], v[120:123], v[188:191], v[12:15]
	v_mfma_f32_16x16x32_bf16 v[8:11], v[132:135], v[188:191], v[8:11]
	v_mfma_f32_16x16x32_bf16 v[60:63], v[128:131], v[168:171], v[60:63]
	v_mfma_f32_16x16x32_bf16 v[56:59], v[136:139], v[168:171], v[56:59]
	v_mfma_f32_16x16x32_bf16 v[44:47], v[128:131], v[176:179], v[44:47]
	v_mfma_f32_16x16x32_bf16 v[40:43], v[136:139], v[176:179], v[40:43]
	v_mfma_f32_16x16x32_bf16 v[28:31], v[128:131], v[184:187], v[28:31]
	v_mfma_f32_16x16x32_bf16 v[24:27], v[136:139], v[184:187], v[24:27]
	v_mfma_f32_16x16x32_bf16 v[12:15], v[128:131], v[214:217], v[12:15]
	v_mfma_f32_16x16x32_bf16 v[8:11], v[136:139], v[214:217], v[8:11]
	v_mfma_f32_16x16x32_bf16 v[52:55], v[140:143], v[164:167], v[52:55]
	v_mfma_f32_16x16x32_bf16 v[48:51], v[156:159], v[164:167], v[48:51]
	v_mfma_f32_16x16x32_bf16 v[36:39], v[140:143], v[172:175], v[36:39]
	v_mfma_f32_16x16x32_bf16 v[32:35], v[156:159], v[172:175], v[32:35]
	v_mfma_f32_16x16x32_bf16 v[20:23], v[140:143], v[180:183], v[20:23]
	v_mfma_f32_16x16x32_bf16 v[16:19], v[156:159], v[180:183], v[16:19]
	v_mfma_f32_16x16x32_bf16 v[4:7], v[140:143], v[188:191], v[4:7]
	v_mfma_f32_16x16x32_bf16 v[0:3], v[156:159], v[188:191], v[0:3]
	v_mfma_f32_16x16x32_bf16 v[52:55], v[144:147], v[168:171], v[52:55]
	v_mfma_f32_16x16x32_bf16 v[48:51], v[160:163], v[168:171], v[48:51]
	v_mfma_f32_16x16x32_bf16 v[36:39], v[144:147], v[176:179], v[36:39]
	v_mfma_f32_16x16x32_bf16 v[32:35], v[160:163], v[176:179], v[32:35]
	v_mfma_f32_16x16x32_bf16 v[20:23], v[144:147], v[184:187], v[20:23]
	v_mfma_f32_16x16x32_bf16 v[16:19], v[160:163], v[184:187], v[16:19]
	v_mfma_f32_16x16x32_bf16 v[4:7], v[144:147], v[214:217], v[4:7]
	v_mfma_f32_16x16x32_bf16 v[0:3], v[160:163], v[214:217], v[0:3]
	s_setprio 0
	s_barrier
	s_mov_b64 s[98:99], s[30:31]
	s_add_u32 s100, s30, 0x100000
	s_addc_u32 s101, s31, 0
	s_add_i32 s30, 0, 0x18000
	s_add_i32 s31, 0, 0x1c000
	ds_read_b128 v[120:123], v116 offset:32768
	ds_read_b128 v[128:131], v116 offset:33792
	ds_read_b128 v[132:135], v116 offset:34816
	ds_read_b128 v[136:139], v116 offset:35840
	ds_read_b128 v[140:143], v116 offset:49152
	ds_read_b128 v[144:147], v116 offset:50176
	ds_read_b128 v[156:159], v116 offset:51200
	ds_read_b128 v[160:163], v116 offset:52224
	ds_read_b128 v[164:167], v248 offset:32768
	ds_read_b128 v[168:171], v248 offset:33792
	ds_read_b128 v[172:175], v248 offset:34816
	ds_read_b128 v[176:179], v248 offset:35840
	ds_read_b128 v[180:183], v248 offset:36864
	ds_read_b128 v[184:187], v248 offset:37888
	s_mov_b32 m0, s43
	ds_read_b128 v[188:191], v248 offset:38912
	global_load_lds_dwordx4 v204, s[100:101]
	s_mov_b32 m0, s44
	ds_read_b128 v[214:217], v248 offset:39936
	global_load_lds_dwordx4 v206, s[100:101]
	s_waitcnt vmcnt(8)
	s_waitcnt lgkmcnt(0)
	s_setprio 1
	s_barrier
	v_mfma_f32_16x16x32_bf16 v[152:155], v[120:123], v[164:167], v[152:155]
	v_mfma_f32_16x16x32_bf16 v[148:151], v[132:135], v[164:167], v[148:151]
	v_mfma_f32_16x16x32_bf16 v[108:111], v[120:123], v[172:175], v[108:111]
	v_mfma_f32_16x16x32_bf16 v[104:107], v[132:135], v[172:175], v[104:107]
	v_mfma_f32_16x16x32_bf16 v[92:95], v[120:123], v[180:183], v[92:95]
	v_mfma_f32_16x16x32_bf16 v[88:91], v[132:135], v[180:183], v[88:91]
	v_mfma_f32_16x16x32_bf16 v[76:79], v[120:123], v[188:191], v[76:79]
	v_mfma_f32_16x16x32_bf16 v[72:75], v[132:135], v[188:191], v[72:75]
	v_mfma_f32_16x16x32_bf16 v[152:155], v[128:131], v[168:171], v[152:155]
	v_mfma_f32_16x16x32_bf16 v[148:151], v[136:139], v[168:171], v[148:151]
	v_mfma_f32_16x16x32_bf16 v[108:111], v[128:131], v[176:179], v[108:111]
	v_mfma_f32_16x16x32_bf16 v[104:107], v[136:139], v[176:179], v[104:107]
	v_mfma_f32_16x16x32_bf16 v[92:95], v[128:131], v[184:187], v[92:95]
	v_mfma_f32_16x16x32_bf16 v[88:91], v[136:139], v[184:187], v[88:91]
	v_mfma_f32_16x16x32_bf16 v[76:79], v[128:131], v[214:217], v[76:79]
	v_mfma_f32_16x16x32_bf16 v[72:75], v[136:139], v[214:217], v[72:75]
	v_mfma_f32_16x16x32_bf16 v[124:127], v[140:143], v[164:167], v[124:127]
	v_mfma_f32_16x16x32_bf16 v[112:115], v[156:159], v[164:167], v[112:115]
	v_mfma_f32_16x16x32_bf16 v[100:103], v[140:143], v[172:175], v[100:103]
	v_mfma_f32_16x16x32_bf16 v[96:99], v[156:159], v[172:175], v[96:99]
	v_mfma_f32_16x16x32_bf16 v[84:87], v[140:143], v[180:183], v[84:87]
	v_mfma_f32_16x16x32_bf16 v[80:83], v[156:159], v[180:183], v[80:83]
	v_mfma_f32_16x16x32_bf16 v[68:71], v[140:143], v[188:191], v[68:71]
	v_mfma_f32_16x16x32_bf16 v[64:67], v[156:159], v[188:191], v[64:67]
	v_mfma_f32_16x16x32_bf16 v[124:127], v[144:147], v[168:171], v[124:127]
	v_mfma_f32_16x16x32_bf16 v[112:115], v[160:163], v[168:171], v[112:115]
	v_mfma_f32_16x16x32_bf16 v[100:103], v[144:147], v[176:179], v[100:103]
	v_mfma_f32_16x16x32_bf16 v[96:99], v[160:163], v[176:179], v[96:99]
	v_mfma_f32_16x16x32_bf16 v[84:87], v[144:147], v[184:187], v[84:87]
	v_mfma_f32_16x16x32_bf16 v[80:83], v[160:163], v[184:187], v[80:83]
	v_mfma_f32_16x16x32_bf16 v[68:71], v[144:147], v[214:217], v[68:71]
	v_mfma_f32_16x16x32_bf16 v[64:67], v[160:163], v[214:217], v[64:67]
	s_setprio 0
	s_barrier
; #define PG8_STAGE(bufoff, gbase, voff) do { _Pragma("unroll") for (int _i = 0; _i < 2; ++_i) \
;         __builtin_amdgcn_global_load_lds((const unsigned*)((const char*)(gbase) + (voff)[_i]), (PG8_LAS unsigned*)(lds + (bufoff) + ldsw + _i * 8192), 16, 0, 0); } while (0)
; #define PG8_LDA(dst, b, h) do { _Pragma("unroll") for (int m = 0; m < 4; ++m) _Pragma("unroll") for (int k = 0; k < 2; ++k) dst[m][k] = *(const PG8_LAS bf16x8*)(lds + PG8_SA(b, h) + aoff + m * 2048 + k * 1024); } while (0)
; #define PG8_MMA(ai, bj, At, Bt) do { __builtin_amdgcn_s_setprio(1); _Pragma("unroll") for (int m = 0; m < 4; ++m) _Pragma("unroll") for (int n = 0; n < 2; ++n) _Pragma("unroll") for (int k = 0; k < 2; ++k) \
;         acc[ai][bj][m][n] = __builtin_amdgcn_mfma_f32_16x16x32_bf16(Bt[n][k], At[m][k], acc[ai][bj][m][n], 0, 0, 0); __builtin_amdgcn_s_setprio(0); } while (0)
; #define PG8_WAIT_V(n) asm volatile("s_waitcnt vmcnt(" #n ")" ::: "memory")
; #define PG8_WAIT_L(n) asm volatile("s_waitcnt lgkmcnt(" #n ")" ::: "memory")
; #define PG8_BAR __builtin_amdgcn_s_barrier()
; #define PG8_SCHED __builtin_amdgcn_sched_barrier(0)
; template <class Epi, class Sched, bool ALIGN_EPI = false, bool SP2 = false>
; __device__ __forceinline__ void gemm_phase(PG8_LAS unsigned char* lds, const Gemm g, const Sched& S, const Epi& E) {
;     ...
;             PG8_STAGE(PG8_SB(1, 0), b3, voffB); PG8_STAGE(PG8_SB(1, 1), b3 + hstep, voffB); PG8_STAGE(PG8_SA(1, 0), a3, voffA); PG8_SCHED; PG8_LDA(At, 1, 1);
;             PG8_WAIT_V(8); PG8_WAIT_L(0); PG8_BAR; PG8_MMA(1, 0, At, B0); PG8_MMA(1, 1, At, B1); PG8_BAR; PG8_SCHED;
;     ...
;         if constexpr (ALIGN_EPI) { if (wr == 0) PG8_BAR; }
	ds_read_b128 v[164:167], v248 offset:49152
	ds_read_b128 v[168:171], v248 offset:50176
	s_add_u32 s100, s28, 0x80
	s_addc_u32 s101, s29, 0
	s_add_u32 s28, s28, 0x100080
	s_addc_u32 s29, s29, 0
	s_add_u32 s98, s98, 0x80
	s_addc_u32 s99, s99, 0
	s_add_i32 m0, s30, s39
	ds_read_b128 v[172:175], v248 offset:51200
	global_load_lds_dwordx4 v194, s[100:101]
	s_add_i32 m0, m0, 0x2000
	ds_read_b128 v[176:179], v248 offset:52224
	global_load_lds_dwordx4 v208, s[100:101]
	s_add_i32 m0, s31, s39
	ds_read_b128 v[180:183], v248 offset:53248
	global_load_lds_dwordx4 v194, s[28:29]
	s_add_i32 m0, m0, 0x2000
	ds_read_b128 v[184:187], v248 offset:54272
	global_load_lds_dwordx4 v208, s[28:29]
	s_mov_b32 m0, s46
	ds_read_b128 v[188:191], v248 offset:55296
	global_load_lds_dwordx4 v204, s[98:99]
	s_mov_b32 m0, s48
	ds_read_b128 v[214:217], v248 offset:56320
	global_load_lds_dwordx4 v206, s[98:99]
	s_waitcnt vmcnt(8)
	s_waitcnt lgkmcnt(0)
	s_setprio 1
	s_barrier
	v_mfma_f32_16x16x32_bf16 v[60:63], v[120:123], v[164:167], v[60:63]
	v_mfma_f32_16x16x32_bf16 v[56:59], v[132:135], v[164:167], v[56:59]
	v_mfma_f32_16x16x32_bf16 v[44:47], v[120:123], v[172:175], v[44:47]
	v_mfma_f32_16x16x32_bf16 v[40:43], v[132:135], v[172:175], v[40:43]
	v_mfma_f32_16x16x32_bf16 v[28:31], v[120:123], v[180:183], v[28:31]
	v_mfma_f32_16x16x32_bf16 v[24:27], v[132:135], v[180:183], v[24:27]
	v_mfma_f32_16x16x32_bf16 v[12:15], v[120:123], v[188:191], v[12:15]
	v_mfma_f32_16x16x32_bf16 v[8:11], v[132:135], v[188:191], v[8:11]
	v_mfma_f32_16x16x32_bf16 v[60:63], v[128:131], v[168:171], v[60:63]
	v_mfma_f32_16x16x32_bf16 v[56:59], v[136:139], v[168:171], v[56:59]
	v_mfma_f32_16x16x32_bf16 v[44:47], v[128:131], v[176:179], v[44:47]
	v_mfma_f32_16x16x32_bf16 v[40:43], v[136:139], v[176:179], v[40:43]
	v_mfma_f32_16x16x32_bf16 v[28:31], v[128:131], v[184:187], v[28:31]
	v_mfma_f32_16x16x32_bf16 v[24:27], v[136:139], v[184:187], v[24:27]
	v_mfma_f32_16x16x32_bf16 v[12:15], v[128:131], v[214:217], v[12:15]
	v_mfma_f32_16x16x32_bf16 v[8:11], v[136:139], v[214:217], v[8:11]
	v_mfma_f32_16x16x32_bf16 v[52:55], v[140:143], v[164:167], v[52:55]
	v_mfma_f32_16x16x32_bf16 v[48:51], v[156:159], v[164:167], v[48:51]
	v_mfma_f32_16x16x32_bf16 v[36:39], v[140:143], v[172:175], v[36:39]
	v_mfma_f32_16x16x32_bf16 v[32:35], v[156:159], v[172:175], v[32:35]
	v_mfma_f32_16x16x32_bf16 v[20:23], v[140:143], v[180:183], v[20:23]
	v_mfma_f32_16x16x32_bf16 v[16:19], v[156:159], v[180:183], v[16:19]
	v_mfma_f32_16x16x32_bf16 v[4:7], v[140:143], v[188:191], v[4:7]
	v_mfma_f32_16x16x32_bf16 v[0:3], v[156:159], v[188:191], v[0:3]
	v_mfma_f32_16x16x32_bf16 v[52:55], v[144:147], v[168:171], v[52:55]
	v_mfma_f32_16x16x32_bf16 v[48:51], v[160:163], v[168:171], v[48:51]
	v_mfma_f32_16x16x32_bf16 v[36:39], v[144:147], v[176:179], v[36:39]
	v_mfma_f32_16x16x32_bf16 v[32:35], v[160:163], v[176:179], v[32:35]
	v_mfma_f32_16x16x32_bf16 v[20:23], v[144:147], v[184:187], v[20:23]
	v_mfma_f32_16x16x32_bf16 v[16:19], v[160:163], v[184:187], v[16:19]
	v_mfma_f32_16x16x32_bf16 v[4:7], v[144:147], v[214:217], v[4:7]
	v_mfma_f32_16x16x32_bf16 v[0:3], v[160:163], v[214:217], v[0:3]
	s_setprio 0
	s_barrier
	s_add_i32 s56, s56, 2
	s_add_u32 s40, s40, 0x100
	s_addc_u32 s41, s41, 0
	s_cmp_gt_u32 s56, 61
	s_cbranch_scc0 .LBB0_965
	s_and_b64 vcc, exec, s[10:11]
	s_cbranch_vccz .LBB0_968
	s_barrier

; #define PG8_STAGE(bufoff, gbase, voff) do { _Pragma("unroll") for (int _i = 0; _i < 2; ++_i) \
;         __builtin_amdgcn_global_load_lds((const unsigned*)((const char*)(gbase) + (voff)[_i]), (PG8_LAS unsigned*)(lds + (bufoff) + ldsw + _i * 8192), 16, 0, 0); } while (0)
; #define PG8_LDA(dst, b, h) do { _Pragma("unroll") for (int m = 0; m < 4; ++m) _Pragma("unroll") for (int k = 0; k < 2; ++k) dst[m][k] = *(const PG8_LAS bf16x8*)(lds + PG8_SA(b, h) + aoff + m * 2048 + k * 1024); } while (0)
; #define PG8_LDB(dst, b, h) do { _Pragma("unroll") for (int n = 0; n < 2; ++n) _Pragma("unroll") for (int k = 0; k < 2; ++k) dst[n][k] = *(const PG8_LAS bf16x8*)(lds + PG8_SB(b, h) + boff + n * 2048 + k * 1024); } while (0)
; #define PG8_WAIT_L(n) asm volatile("s_waitcnt lgkmcnt(" #n ")" ::: "memory")
; #define PG8_WAIT_V8_UNLESS(flag) asm volatile("s_cmp_lg_i32 %0, 0\n\ts_cbranch_scc1 .Lpg8rx%=\n\ts_waitcnt vmcnt(8)\n.Lpg8rx%=:" :: "s"(__builtin_amdgcn_readfirstlane(flag)) : "scc", "memory")
; template <class Epi, class Sched, bool ALIGN_EPI = false, bool SP2 = false>
; __device__ __forceinline__ void gemm_phase(PG8_LAS unsigned char* lds, const Gemm g, const Sched& S, const Epi& E) {
;     ...
;         const char* nA = has_next ? (const char*)g.A + (size_t)nxt.pm * tstep : cA; const char* nB = has_next ? (const char*)g.Bt + (size_t)nxt.pn * tstep : cB;
;         for (int t = 0; t < nt; t += 2) {
;             const bool last = (t == nt - 2);
;             const char* a1 = cA + (size_t)(t + 1) * kstep;
;             const char* a2 = last ? nA : cA + (size_t)(t + 2) * kstep; const char* b2 = last ? nB : cB + (size_t)(t + 2) * kstep;
;             const char* a3 = a2 + kstep; const char* b3 = b2 + kstep;
;             if (last && has_next) S.a_ready(nxt);
;             if constexpr (SP2) {
;             const int rx = (relax && t == 0) ? 1 : 0;
;             PG8_STAGE(PG8_SA(1, 1), a1 + hstep, voffA); PG8_SCHED; PG8_LDB(B0, 0, 0); PG8_LDB(B1, 0, 1); PG8_SCHED; PG8_LDA(At, 0, 0);
;             PG8_WAIT_V8_UNLESS(rx); PG8_WAIT_L(0); PG8_BAR; PG8_MMA(0, 0, At, B0); PG8_MMA(0, 1, At, B1); PG8_BAR; PG8_SCHED;
;     ...
;         for (int a = 0; a < 2; ++a)
; #pragma unroll
;             for (int b = 0; b < 2; ++b)
; #pragma unroll
;                 for (int m = 0; m < 4; ++m)
; #pragma unroll
;                     for (int n = 0; n < 2; ++n) acc[a][b][m][n] = (f32x4){0.f, 0.f, 0.f, 0.f};
.LBB0_1132:
	s_ashr_i32 s19, s18, 31
	s_lshl_b64 s[22:23], s[18:19], 19
	s_add_u32 s22, s6, s22
	s_addc_u32 s23, s7, s23
	s_and_b64 s[24:25], s[20:21], exec
	s_cselect_b32 s19, s23, s43
	s_cselect_b32 s27, s22, s42
	s_ashr_i32 s17, s16, 31
	s_lshl_b64 s[24:25], s[16:17], 19
	s_add_u32 s24, s44, s24
	s_addc_u32 s25, s46, s25
	s_and_b64 s[30:31], s[20:21], exec
	s_cselect_b32 s17, s25, s29
	s_cselect_b32 s34, s24, s28
	s_add_u32 s30, s42, 0x40080
	s_addc_u32 s31, s43, 0
	s_add_u32 s57, s28, 0x100
	v_mov_b32_e32 v0, 0
	v_lshl_add_u64 v[128:129], s[30:31], 0, v[156:157]
	v_lshl_add_u64 v[130:131], s[30:31], 0, v[158:159]
	s_addc_u32 s58, s29, 0
	s_mov_b32 s59, -2
	s_mov_b64 vcc, 0
	s_waitcnt lgkmcnt(0)
	v_mov_b32_e32 v1, v0
	v_mov_b32_e32 v2, v0
	v_mov_b32_e32 v3, v0
	v_mov_b32_e32 v4, v0
	v_mov_b32_e32 v5, v0
	v_mov_b32_e32 v6, v0
	v_mov_b32_e32 v7, v0
	v_mov_b32_e32 v16, v0
	v_mov_b32_e32 v17, v0
	v_mov_b32_e32 v18, v0
	v_mov_b32_e32 v19, v0
	v_mov_b32_e32 v20, v0
	v_mov_b32_e32 v21, v0
	v_mov_b32_e32 v22, v0
	v_mov_b32_e32 v23, v0
	v_mov_b32_e32 v32, v0
	v_mov_b32_e32 v33, v0
	v_mov_b32_e32 v34, v0
	v_mov_b32_e32 v35, v0
	v_mov_b32_e32 v36, v0
	v_mov_b32_e32 v37, v0
	v_mov_b32_e32 v38, v0
	v_mov_b32_e32 v39, v0
	v_mov_b32_e32 v48, v0
	v_mov_b32_e32 v49, v0
	v_mov_b32_e32 v50, v0
	v_mov_b32_e32 v51, v0
	v_mov_b32_e32 v52, v0
	v_mov_b32_e32 v53, v0
	v_mov_b32_e32 v54, v0
	v_mov_b32_e32 v55, v0
	v_mov_b32_e32 v8, v0
	v_mov_b32_e32 v9, v0
	v_mov_b32_e32 v10, v0
	v_mov_b32_e32 v11, v0
	v_mov_b32_e32 v12, v0
	v_mov_b32_e32 v13, v0
	v_mov_b32_e32 v14, v0
	v_mov_b32_e32 v15, v0
	v_mov_b32_e32 v24, v0
	v_mov_b32_e32 v25, v0
	v_mov_b32_e32 v26, v0
	v_mov_b32_e32 v27, v0
	v_mov_b32_e32 v28, v0
	v_mov_b32_e32 v29, v0
	v_mov_b32_e32 v30, v0
	v_mov_b32_e32 v31, v0
	v_mov_b32_e32 v40, v0
	v_mov_b32_e32 v41, v0
	v_mov_b32_e32 v42, v0
	v_mov_b32_e32 v43, v0
	v_mov_b32_e32 v44, v0
	v_mov_b32_e32 v45, v0
	v_mov_b32_e32 v46, v0
	v_mov_b32_e32 v47, v0
	v_mov_b32_e32 v56, v0
	v_mov_b32_e32 v57, v0
	v_mov_b32_e32 v58, v0
	v_mov_b32_e32 v59, v0
	v_mov_b32_e32 v60, v0
	v_mov_b32_e32 v61, v0
	v_mov_b32_e32 v62, v0
	v_mov_b32_e32 v63, v0
	v_mov_b32_e32 v64, v0
	v_mov_b32_e32 v65, v0
	v_mov_b32_e32 v66, v0
	v_mov_b32_e32 v67, v0
	v_mov_b32_e32 v68, v0
	v_mov_b32_e32 v69, v0
	v_mov_b32_e32 v70, v0
	v_mov_b32_e32 v71, v0
	v_mov_b32_e32 v80, v0
	v_mov_b32_e32 v81, v0
	v_mov_b32_e32 v82, v0
	v_mov_b32_e32 v83, v0
	v_mov_b32_e32 v84, v0
	v_mov_b32_e32 v85, v0
	v_mov_b32_e32 v86, v0
	v_mov_b32_e32 v87, v0
	v_mov_b32_e32 v96, v0
	v_mov_b32_e32 v97, v0
	v_mov_b32_e32 v98, v0
	v_mov_b32_e32 v99, v0
	v_mov_b32_e32 v100, v0
	v_mov_b32_e32 v101, v0
	v_mov_b32_e32 v102, v0
	v_mov_b32_e32 v103, v0
	v_mov_b32_e32 v112, v0
	v_mov_b32_e32 v113, v0
	v_mov_b32_e32 v114, v0
	v_mov_b32_e32 v115, v0
	v_mov_b32_e32 v116, v0
	v_mov_b32_e32 v117, v0
	v_mov_b32_e32 v118, v0
	v_mov_b32_e32 v119, v0
	v_mov_b32_e32 v72, v0
	v_mov_b32_e32 v73, v0
	v_mov_b32_e32 v74, v0
	v_mov_b32_e32 v75, v0
	v_mov_b32_e32 v76, v0
	v_mov_b32_e32 v77, v0
	v_mov_b32_e32 v78, v0
	v_mov_b32_e32 v79, v0
	v_mov_b32_e32 v88, v0
	v_mov_b32_e32 v89, v0
	v_mov_b32_e32 v90, v0
	v_mov_b32_e32 v91, v0
	v_mov_b32_e32 v92, v0
	v_mov_b32_e32 v93, v0
	v_mov_b32_e32 v94, v0
	v_mov_b32_e32 v95, v0
	v_mov_b32_e32 v104, v0
	v_mov_b32_e32 v105, v0
	v_mov_b32_e32 v106, v0
	v_mov_b32_e32 v107, v0
	v_mov_b32_e32 v108, v0
	v_mov_b32_e32 v109, v0
	v_mov_b32_e32 v110, v0
	v_mov_b32_e32 v111, v0
	v_mov_b32_e32 v120, v0
	v_mov_b32_e32 v121, v0
	v_mov_b32_e32 v122, v0
	v_mov_b32_e32 v123, v0
	v_mov_b32_e32 v124, v0
	v_mov_b32_e32 v125, v0
	v_mov_b32_e32 v126, v0
	v_mov_b32_e32 v127, v0
	v_add_u32_e32 v128, 0x10000, v174
.LBB0_1133:
	s_add_u32 s28, s42, vcc_lo
	s_addc_u32 s29, s43, vcc_hi
	s_add_u32 s30, s28, 0x100
	s_addc_u32 s31, s29, 0
	s_add_u32 s98, s28, 0x40080
	s_addc_u32 s99, s29, 0
	s_add_u32 s65, s57, vcc_lo
	s_addc_u32 s66, s58, vcc_hi
	s_cmp_eq_u32 vcc_lo, 0
	s_cselect_b64 s[28:29], -1, 0
	s_and_b64 s[60:61], s[62:63], s[28:29]
	s_cmpk_eq_i32 vcc_lo, 0x700
	s_cselect_b32 s31, s19, s31
	s_cselect_b32 s30, s27, s30
	s_cselect_b32 s29, s17, s66
	s_cselect_b32 s28, s34, s65
	s_add_i32 s65, 0, 0x10000
	s_add_i32 s66, 0, 0x14000
	ds_read_b128 v[132:135], v128
	ds_read_b128 v[136:139], v128 offset:1024
	ds_read_b128 v[140:143], v128 offset:2048
	ds_read_b128 v[144:147], v128 offset:3072
	ds_read_b128 v[160:163], v128 offset:16384
	ds_read_b128 v[164:167], v128 offset:17408
	ds_read_b128 v[168:171], v128 offset:18432
	ds_read_b128 v[176:179], v128 offset:19456
	ds_read_b128 v[180:183], v175
	ds_read_b128 v[184:187], v175 offset:1024
	ds_read_b128 v[188:191], v175 offset:2048
	ds_read_b128 v[204:207], v175 offset:3072
	ds_read_b128 v[208:211], v175 offset:4096
	ds_read_b128 v[212:215], v175 offset:5120
	ds_read_b128 v[216:219], v175 offset:6144
	s_add_i32 m0, s41, 0xc000
	s_and_b32 s67, s60, 1
	global_load_lds_dwordx4 v148, s[98:99]
	s_add_i32 m0, s41, 0xe000
	ds_read_b128 v[220:223], v175 offset:7168
	global_load_lds_dwordx4 v152, s[98:99]
	s_cmp_lg_i32 s67, 0
	s_cbranch_scc1 .Lpg8rx10
	s_waitcnt vmcnt(8)

; #define PG8_STAGE(bufoff, gbase, voff) do { _Pragma("unroll") for (int _i = 0; _i < 2; ++_i) \
;         __builtin_amdgcn_global_load_lds((const unsigned*)((const char*)(gbase) + (voff)[_i]), (PG8_LAS unsigned*)(lds + (bufoff) + ldsw + _i * 8192), 16, 0, 0); } while (0)
; #define PG8_LDA(dst, b, h) do { _Pragma("unroll") for (int m = 0; m < 4; ++m) _Pragma("unroll") for (int k = 0; k < 2; ++k) dst[m][k] = *(const PG8_LAS bf16x8*)(lds + PG8_SA(b, h) + aoff + m * 2048 + k * 1024); } while (0)
; #define PG8_LDB(dst, b, h) do { _Pragma("unroll") for (int n = 0; n < 2; ++n) _Pragma("unroll") for (int k = 0; k < 2; ++k) dst[n][k] = *(const PG8_LAS bf16x8*)(lds + PG8_SB(b, h) + boff + n * 2048 + k * 1024); } while (0)
; #define PG8_MMA(ai, bj, At, Bt) do { __builtin_amdgcn_s_setprio(1); _Pragma("unroll") for (int m = 0; m < 4; ++m) _Pragma("unroll") for (int n = 0; n < 2; ++n) _Pragma("unroll") for (int k = 0; k < 2; ++k) \
;         acc[ai][bj][m][n] = __builtin_amdgcn_mfma_f32_16x16x32_bf16(Bt[n][k], At[m][k], acc[ai][bj][m][n], 0, 0, 0); __builtin_amdgcn_s_setprio(0); } while (0)
; #define PG8_WAIT_V(n) asm volatile("s_waitcnt vmcnt(" #n ")" ::: "memory")
; #define PG8_WAIT_L(n) asm volatile("s_waitcnt lgkmcnt(" #n ")" ::: "memory")
; #define PG8_WAIT_V8_UNLESS(flag) asm volatile("s_cmp_lg_i32 %0, 0\n\ts_cbranch_scc1 .Lpg8rx%=\n\ts_waitcnt vmcnt(8)\n.Lpg8rx%=:" :: "s"(__builtin_amdgcn_readfirstlane(flag)) : "scc", "memory")
; #define PG8_BAR __builtin_amdgcn_s_barrier()
; #define PG8_SCHED __builtin_amdgcn_sched_barrier(0)
; template <class Epi, class Sched, bool ALIGN_EPI = false, bool SP2 = false>
; __device__ __forceinline__ void gemm_phase(PG8_LAS unsigned char* lds, const Gemm g, const Sched& S, const Epi& E) {
;     ...
;             PG8_WAIT_V8_UNLESS(rx); PG8_WAIT_L(0); PG8_BAR; PG8_MMA(1, 0, At, B0); PG8_MMA(1, 1, At, B1); PG8_BAR; PG8_SCHED;
;             PG8_STAGE(PG8_SA(0, 1), a2 + hstep, voffA); PG8_SCHED; PG8_LDB(B0, 1, 0); PG8_LDB(B1, 1, 1); PG8_SCHED; PG8_LDA(At, 1, 0);
;             PG8_WAIT_V(8); PG8_WAIT_L(0); PG8_BAR; PG8_MMA(0, 0, At, B0); PG8_MMA(0, 1, At, B1); PG8_BAR; PG8_SCHED;
.Lpg8rx11:
	s_waitcnt lgkmcnt(0)
	s_setprio 1
	s_barrier
	v_mfma_f32_16x16x32_bf16 v[60:63], v[132:135], v[180:183], v[60:63]
	v_mfma_f32_16x16x32_bf16 v[56:59], v[140:143], v[180:183], v[56:59]
	v_mfma_f32_16x16x32_bf16 v[44:47], v[132:135], v[188:191], v[44:47]
	v_mfma_f32_16x16x32_bf16 v[40:43], v[140:143], v[188:191], v[40:43]
	v_mfma_f32_16x16x32_bf16 v[28:31], v[132:135], v[208:211], v[28:31]
	v_mfma_f32_16x16x32_bf16 v[24:27], v[140:143], v[208:211], v[24:27]
	v_mfma_f32_16x16x32_bf16 v[12:15], v[132:135], v[216:219], v[12:15]
	v_mfma_f32_16x16x32_bf16 v[8:11], v[140:143], v[216:219], v[8:11]
	v_mfma_f32_16x16x32_bf16 v[60:63], v[136:139], v[184:187], v[60:63]
	v_mfma_f32_16x16x32_bf16 v[56:59], v[144:147], v[184:187], v[56:59]
	v_mfma_f32_16x16x32_bf16 v[44:47], v[136:139], v[204:207], v[44:47]
	v_mfma_f32_16x16x32_bf16 v[40:43], v[144:147], v[204:207], v[40:43]
	v_mfma_f32_16x16x32_bf16 v[28:31], v[136:139], v[212:215], v[28:31]
	v_mfma_f32_16x16x32_bf16 v[24:27], v[144:147], v[212:215], v[24:27]
	v_mfma_f32_16x16x32_bf16 v[12:15], v[136:139], v[220:223], v[12:15]
	v_mfma_f32_16x16x32_bf16 v[8:11], v[144:147], v[220:223], v[8:11]
	v_mfma_f32_16x16x32_bf16 v[52:55], v[160:163], v[180:183], v[52:55]
	v_mfma_f32_16x16x32_bf16 v[48:51], v[168:171], v[180:183], v[48:51]
	v_mfma_f32_16x16x32_bf16 v[36:39], v[160:163], v[188:191], v[36:39]
	v_mfma_f32_16x16x32_bf16 v[32:35], v[168:171], v[188:191], v[32:35]
	v_mfma_f32_16x16x32_bf16 v[20:23], v[160:163], v[208:211], v[20:23]
	v_mfma_f32_16x16x32_bf16 v[16:19], v[168:171], v[208:211], v[16:19]
	v_mfma_f32_16x16x32_bf16 v[4:7], v[160:163], v[216:219], v[4:7]
	v_mfma_f32_16x16x32_bf16 v[0:3], v[168:171], v[216:219], v[0:3]
	v_mfma_f32_16x16x32_bf16 v[52:55], v[164:167], v[184:187], v[52:55]
	v_mfma_f32_16x16x32_bf16 v[48:51], v[176:179], v[184:187], v[48:51]
	v_mfma_f32_16x16x32_bf16 v[36:39], v[164:167], v[204:207], v[36:39]
	v_mfma_f32_16x16x32_bf16 v[32:35], v[176:179], v[204:207], v[32:35]
	v_mfma_f32_16x16x32_bf16 v[20:23], v[164:167], v[212:215], v[20:23]
	v_mfma_f32_16x16x32_bf16 v[16:19], v[176:179], v[212:215], v[16:19]
	v_mfma_f32_16x16x32_bf16 v[4:7], v[164:167], v[220:223], v[4:7]
	v_mfma_f32_16x16x32_bf16 v[0:3], v[176:179], v[220:223], v[0:3]
	s_setprio 0
	s_barrier
	s_mov_b64 s[98:99], s[30:31]
	s_add_u32 s100, s30, 0x40000
	s_addc_u32 s101, s31, 0
	s_add_i32 s30, 0, 0x18000
	s_add_i32 s31, 0, 0x1c000
	ds_read_b128 v[132:135], v128 offset:32768
	ds_read_b128 v[136:139], v128 offset:33792
	ds_read_b128 v[140:143], v128 offset:34816
	ds_read_b128 v[144:147], v128 offset:35840
	ds_read_b128 v[160:163], v128 offset:49152
	ds_read_b128 v[164:167], v128 offset:50176
	ds_read_b128 v[168:171], v128 offset:51200
	ds_read_b128 v[176:179], v128 offset:52224
	ds_read_b128 v[180:183], v175 offset:32768
	ds_read_b128 v[184:187], v175 offset:33792
	ds_read_b128 v[188:191], v175 offset:34816
	ds_read_b128 v[204:207], v175 offset:35840
	ds_read_b128 v[208:211], v175 offset:36864
	ds_read_b128 v[212:215], v175 offset:37888
	s_mov_b32 m0, s50
	ds_read_b128 v[216:219], v175 offset:38912
	global_load_lds_dwordx4 v148, s[100:101]
	s_mov_b32 m0, s51
	ds_read_b128 v[220:223], v175 offset:39936
	global_load_lds_dwordx4 v152, s[100:101]
	s_waitcnt vmcnt(8)
	s_waitcnt lgkmcnt(0)
	s_setprio 1
	s_barrier
	v_mfma_f32_16x16x32_bf16 v[124:127], v[132:135], v[180:183], v[124:127]
	v_mfma_f32_16x16x32_bf16 v[120:123], v[140:143], v[180:183], v[120:123]
	v_mfma_f32_16x16x32_bf16 v[108:111], v[132:135], v[188:191], v[108:111]
	v_mfma_f32_16x16x32_bf16 v[104:107], v[140:143], v[188:191], v[104:107]
	v_mfma_f32_16x16x32_bf16 v[92:95], v[132:135], v[208:211], v[92:95]
	v_mfma_f32_16x16x32_bf16 v[88:91], v[140:143], v[208:211], v[88:91]
	v_mfma_f32_16x16x32_bf16 v[76:79], v[132:135], v[216:219], v[76:79]
	v_mfma_f32_16x16x32_bf16 v[72:75], v[140:143], v[216:219], v[72:75]
	v_mfma_f32_16x16x32_bf16 v[124:127], v[136:139], v[184:187], v[124:127]
	v_mfma_f32_16x16x32_bf16 v[120:123], v[144:147], v[184:187], v[120:123]
	v_mfma_f32_16x16x32_bf16 v[108:111], v[136:139], v[204:207], v[108:111]
	v_mfma_f32_16x16x32_bf16 v[104:107], v[144:147], v[204:207], v[104:107]
	v_mfma_f32_16x16x32_bf16 v[92:95], v[136:139], v[212:215], v[92:95]
	v_mfma_f32_16x16x32_bf16 v[88:91], v[144:147], v[212:215], v[88:91]
	v_mfma_f32_16x16x32_bf16 v[76:79], v[136:139], v[220:223], v[76:79]
	v_mfma_f32_16x16x32_bf16 v[72:75], v[144:147], v[220:223], v[72:75]
	v_mfma_f32_16x16x32_bf16 v[116:119], v[160:163], v[180:183], v[116:119]
	v_mfma_f32_16x16x32_bf16 v[112:115], v[168:171], v[180:183], v[112:115]
	v_mfma_f32_16x16x32_bf16 v[100:103], v[160:163], v[188:191], v[100:103]
	v_mfma_f32_16x16x32_bf16 v[96:99], v[168:171], v[188:191], v[96:99]
	v_mfma_f32_16x16x32_bf16 v[84:87], v[160:163], v[208:211], v[84:87]
	v_mfma_f32_16x16x32_bf16 v[80:83], v[168:171], v[208:211], v[80:83]
	v_mfma_f32_16x16x32_bf16 v[68:71], v[160:163], v[216:219], v[68:71]
	v_mfma_f32_16x16x32_bf16 v[64:67], v[168:171], v[216:219], v[64:67]
	v_mfma_f32_16x16x32_bf16 v[116:119], v[164:167], v[184:187], v[116:119]
	v_mfma_f32_16x16x32_bf16 v[112:115], v[176:179], v[184:187], v[112:115]
	v_mfma_f32_16x16x32_bf16 v[100:103], v[164:167], v[204:207], v[100:103]
	v_mfma_f32_16x16x32_bf16 v[96:99], v[176:179], v[204:207], v[96:99]
	v_mfma_f32_16x16x32_bf16 v[84:87], v[164:167], v[212:215], v[84:87]
	v_mfma_f32_16x16x32_bf16 v[80:83], v[176:179], v[212:215], v[80:83]
	v_mfma_f32_16x16x32_bf16 v[68:71], v[164:167], v[220:223], v[68:71]
	v_mfma_f32_16x16x32_bf16 v[64:67], v[176:179], v[220:223], v[64:67]
	s_setprio 0
	s_barrier
; #define PG8_STAGE(bufoff, gbase, voff) do { _Pragma("unroll") for (int _i = 0; _i < 2; ++_i) \
;         __builtin_amdgcn_global_load_lds((const unsigned*)((const char*)(gbase) + (voff)[_i]), (PG8_LAS unsigned*)(lds + (bufoff) + ldsw + _i * 8192), 16, 0, 0); } while (0)
; #define PG8_LDA(dst, b, h) do { _Pragma("unroll") for (int m = 0; m < 4; ++m) _Pragma("unroll") for (int k = 0; k < 2; ++k) dst[m][k] = *(const PG8_LAS bf16x8*)(lds + PG8_SA(b, h) + aoff + m * 2048 + k * 1024); } while (0)
; #define PG8_MMA(ai, bj, At, Bt) do { __builtin_amdgcn_s_setprio(1); _Pragma("unroll") for (int m = 0; m < 4; ++m) _Pragma("unroll") for (int n = 0; n < 2; ++n) _Pragma("unroll") for (int k = 0; k < 2; ++k) \
;         acc[ai][bj][m][n] = __builtin_amdgcn_mfma_f32_16x16x32_bf16(Bt[n][k], At[m][k], acc[ai][bj][m][n], 0, 0, 0); __builtin_amdgcn_s_setprio(0); } while (0)
; #define PG8_WAIT_V(n) asm volatile("s_waitcnt vmcnt(" #n ")" ::: "memory")
; #define PG8_WAIT_L(n) asm volatile("s_waitcnt lgkmcnt(" #n ")" ::: "memory")
; #define PG8_BAR __builtin_amdgcn_s_barrier()
; #define PG8_SCHED __builtin_amdgcn_sched_barrier(0)
; template <class Epi, class Sched, bool ALIGN_EPI = false, bool SP2 = false>
; __device__ __forceinline__ void gemm_phase(PG8_LAS unsigned char* lds, const Gemm g, const Sched& S, const Epi& E) {
;     ...
;             PG8_STAGE(PG8_SB(1, 0), b3, voffB); PG8_STAGE(PG8_SB(1, 1), b3 + hstep, voffB); PG8_STAGE(PG8_SA(1, 0), a3, voffA); PG8_SCHED; PG8_LDA(At, 1, 1);
;             PG8_WAIT_V(8); PG8_WAIT_L(0); PG8_BAR; PG8_MMA(1, 0, At, B0); PG8_MMA(1, 1, At, B1); PG8_BAR; PG8_SCHED;
;     ...
;         if constexpr (ALIGN_EPI) { if (wr == 0) PG8_BAR; }
	ds_read_b128 v[180:183], v175 offset:49152
	ds_read_b128 v[184:187], v175 offset:50176
	s_add_u32 s100, s28, 0x80
	s_addc_u32 s101, s29, 0
	s_add_u32 s28, s28, 0x40080
	s_addc_u32 s29, s29, 0
	s_add_u32 s98, s98, 0x80
	s_addc_u32 s99, s99, 0
	s_add_i32 m0, s30, s35
	ds_read_b128 v[188:191], v175 offset:51200
	global_load_lds_dwordx4 v150, s[100:101]
	s_add_i32 m0, m0, 0x2000
	ds_read_b128 v[204:207], v175 offset:52224
	global_load_lds_dwordx4 v154, s[100:101]
	s_add_i32 m0, s31, s35
	ds_read_b128 v[208:211], v175 offset:53248
	global_load_lds_dwordx4 v150, s[28:29]
	s_add_i32 m0, m0, 0x2000
	ds_read_b128 v[212:215], v175 offset:54272
	global_load_lds_dwordx4 v154, s[28:29]
	s_mov_b32 m0, s52
	ds_read_b128 v[216:219], v175 offset:55296
	global_load_lds_dwordx4 v148, s[98:99]
	s_mov_b32 m0, s53
	ds_read_b128 v[220:223], v175 offset:56320
	global_load_lds_dwordx4 v152, s[98:99]
	s_waitcnt vmcnt(8)
	s_waitcnt lgkmcnt(0)
	s_setprio 1
	s_barrier
	v_mfma_f32_16x16x32_bf16 v[60:63], v[132:135], v[180:183], v[60:63]
	v_mfma_f32_16x16x32_bf16 v[56:59], v[140:143], v[180:183], v[56:59]
	v_mfma_f32_16x16x32_bf16 v[44:47], v[132:135], v[188:191], v[44:47]
	v_mfma_f32_16x16x32_bf16 v[40:43], v[140:143], v[188:191], v[40:43]
	v_mfma_f32_16x16x32_bf16 v[28:31], v[132:135], v[208:211], v[28:31]
	v_mfma_f32_16x16x32_bf16 v[24:27], v[140:143], v[208:211], v[24:27]
	v_mfma_f32_16x16x32_bf16 v[12:15], v[132:135], v[216:219], v[12:15]
	v_mfma_f32_16x16x32_bf16 v[8:11], v[140:143], v[216:219], v[8:11]
	v_mfma_f32_16x16x32_bf16 v[60:63], v[136:139], v[184:187], v[60:63]
	v_mfma_f32_16x16x32_bf16 v[56:59], v[144:147], v[184:187], v[56:59]
	v_mfma_f32_16x16x32_bf16 v[44:47], v[136:139], v[204:207], v[44:47]
	v_mfma_f32_16x16x32_bf16 v[40:43], v[144:147], v[204:207], v[40:43]
	v_mfma_f32_16x16x32_bf16 v[28:31], v[136:139], v[212:215], v[28:31]
	v_mfma_f32_16x16x32_bf16 v[24:27], v[144:147], v[212:215], v[24:27]
	v_mfma_f32_16x16x32_bf16 v[12:15], v[136:139], v[220:223], v[12:15]
	v_mfma_f32_16x16x32_bf16 v[8:11], v[144:147], v[220:223], v[8:11]
	v_mfma_f32_16x16x32_bf16 v[52:55], v[160:163], v[180:183], v[52:55]
	v_mfma_f32_16x16x32_bf16 v[48:51], v[168:171], v[180:183], v[48:51]
	v_mfma_f32_16x16x32_bf16 v[36:39], v[160:163], v[188:191], v[36:39]
	v_mfma_f32_16x16x32_bf16 v[32:35], v[168:171], v[188:191], v[32:35]
	v_mfma_f32_16x16x32_bf16 v[20:23], v[160:163], v[208:211], v[20:23]
	v_mfma_f32_16x16x32_bf16 v[16:19], v[168:171], v[208:211], v[16:19]
	v_mfma_f32_16x16x32_bf16 v[4:7], v[160:163], v[216:219], v[4:7]
	v_mfma_f32_16x16x32_bf16 v[0:3], v[168:171], v[216:219], v[0:3]
	v_mfma_f32_16x16x32_bf16 v[52:55], v[164:167], v[184:187], v[52:55]
	v_mfma_f32_16x16x32_bf16 v[48:51], v[176:179], v[184:187], v[48:51]
	v_mfma_f32_16x16x32_bf16 v[36:39], v[164:167], v[204:207], v[36:39]
	v_mfma_f32_16x16x32_bf16 v[32:35], v[176:179], v[204:207], v[32:35]
	v_mfma_f32_16x16x32_bf16 v[20:23], v[164:167], v[212:215], v[20:23]
	v_mfma_f32_16x16x32_bf16 v[16:19], v[176:179], v[212:215], v[16:19]
	v_mfma_f32_16x16x32_bf16 v[4:7], v[164:167], v[220:223], v[4:7]
	v_mfma_f32_16x16x32_bf16 v[0:3], v[176:179], v[220:223], v[0:3]
	s_setprio 0
	s_barrier
	s_add_i32 s59, s59, 2
	s_add_u32 vcc_lo, vcc_lo, 0x100
	s_addc_u32 vcc_hi, vcc_hi, 0
	s_cmp_gt_u32 s59, 13
	s_cbranch_scc0 .LBB0_1133
	s_and_b64 vcc, exec, s[14:15]
	s_cbranch_vccz .LBB0_1136
	s_barrier
